# GEMM loops: s_setprio 1 moved in front of the phase barrier (24 sites) so the MFMA block starts at raised priority
# speedup vs baseline: 1.0072x; 1.0072x over previous
; #define PG8_STAGE(bufoff, gbase, voff) do { _Pragma("unroll") for (int _i = 0; _i < 2; ++_i) \
;         __builtin_amdgcn_global_load_lds((const unsigned*)((const char*)(gbase) + (voff)[_i]), (LAS unsigned*)(lds + (bufoff) + ldsw + _i * 8192), 16, 0, 0); } while (0)
; #define PG8_LDA(dst, b, h) do { _Pragma("unroll") for (int m = 0; m < 4; ++m) _Pragma("unroll") for (int k = 0; k < 2; ++k) dst[m][k] = *(const LAS bf16x8*)(lds + PG8_SA(b, h) + aoff + m * 2048 + k * 1024); } while (0)
; #define PG8_LDB(dst, b, h) do { _Pragma("unroll") for (int n = 0; n < 2; ++n) _Pragma("unroll") for (int k = 0; k < 2; ++k) dst[n][k] = *(const LAS bf16x8*)(lds + PG8_SB(b, h) + boff + n * 2048 + k * 1024); } while (0)
; #define PG8_MMA(ai, bj, At, Bt) do { __builtin_amdgcn_s_setprio(1); _Pragma("unroll") for (int m = 0; m < 4; ++m) _Pragma("unroll") for (int n = 0; n < 2; ++n) _Pragma("unroll") for (int k = 0; k < 2; ++k) \
;         acc[ai][bj][m][n] = __builtin_amdgcn_mfma_f32_16x16x32_bf16(Bt[n][k], At[m][k], acc[ai][bj][m][n], 0, 0, 0); __builtin_amdgcn_s_setprio(0); } while (0)
; #define PG8_WAIT_V(n) asm volatile("s_waitcnt vmcnt(" #n ")" ::: "memory")
; #define PG8_WAIT_L(n) asm volatile("s_waitcnt lgkmcnt(" #n ")" ::: "memory")
; #define PG8_BAR __builtin_amdgcn_s_barrier()
; #define PG8_SCHED __builtin_amdgcn_sched_barrier(0)
; template <class Epi, class Sched, bool ALIGN_EPI = false, bool SP2 = false>
; __device__ __forceinline__ void gemm_phase(LAS unsigned char* lds, const Gemm g, const Sched& S, const Epi& E) {
;     ...
;             const bool last = (t == nt - 2);
;             const char* a1 = cA + (size_t)(t + 1) * kstep;
;             const char* a2 = last ? nA : cA + (size_t)(t + 2) * kstep; const char* b2 = last ? nB : cB + (size_t)(t + 2) * kstep;
;             const char* a3 = a2 + kstep; const char* b3 = b2 + kstep;
;             if (last && has_next) S.a_ready(nxt);
;             if constexpr (SP2) {
;             PG8_LDB(B0, 0, 0); PG8_LDB(B1, 0, 1); PG8_SCHED; PG8_LDA(At, 0, 0); PG8_STAGE(PG8_SA(1, 1), a1 + hstepA, voffA);
;             PG8_WAIT_V(8); PG8_WAIT_L(0); PG8_BAR; PG8_MMA(0, 0, At, B0); PG8_MMA(0, 1, At, B1); PG8_BAR; PG8_SCHED;
;             PG8_LDA(At, 0, 1); PG8_STAGE(PG8_SB(0, 0), b2, voffB); PG8_STAGE(PG8_SB(0, 1), b2 + hstepB, voffB); PG8_STAGE(PG8_SA(0, 0), a2, voffA);
.LBB0_349:
	ds_read_b128 v[156:159], v149
	ds_read_b128 v[160:163], v149 offset:1024
	ds_read_b128 v[164:167], v149 offset:2048
	ds_read_b128 v[168:171], v149 offset:3072
	ds_read_b128 v[172:175], v150
	ds_read_b128 v[176:179], v150 offset:1024
	ds_read_b128 v[180:183], v150 offset:2048
	ds_read_b128 v[184:187], v150 offset:3072
	s_add_u32 s24, s22, 0xfff80080
	s_addc_u32 s25, s23, -1
	s_cmp_eq_u32 s58, 28
	s_cselect_b32 s27, s15, s25
	s_cselect_b32 s26, s47, s24
	s_cselect_b32 s25, s13, s55
	s_cselect_b32 s24, s50, s51
	v_lshl_add_u64 v[146:147], s[22:23], 0, v[138:139]
	s_add_i32 m0, s21, 0xc000
	ds_read_b128 v[188:191], v151
	ds_read_b128 v[192:195], v151 offset:1024
	ds_read_b128 v[196:199], v151 offset:2048
	ds_read_b128 v[200:203], v151 offset:3072
	ds_read_b128 v[204:207], v151 offset:4096
	ds_read_b128 v[208:211], v151 offset:5120
	ds_read_b128 v[212:215], v151 offset:6144
	ds_read_b128 v[216:219], v151 offset:7168
	global_load_lds_dwordx4 v[146:147], off
	v_lshl_add_u64 v[146:147], s[22:23], 0, v[140:141]
	s_add_i32 m0, s21, 0xe000
	s_nop 0
	global_load_lds_dwordx4 v[146:147], off
	s_waitcnt vmcnt(8)
	s_waitcnt lgkmcnt(0)
	s_setprio 1
	s_barrier
	s_waitcnt lgkmcnt(0)
	v_mfma_f32_16x16x32_bf16 v[126:129], v[156:159], v[188:191], v[126:129]
	v_mfma_f32_16x16x32_bf16 v[122:125], v[164:167], v[188:191], v[122:125]
	v_mfma_f32_16x16x32_bf16 v[118:121], v[156:159], v[196:199], v[118:121]
	v_mfma_f32_16x16x32_bf16 v[110:113], v[164:167], v[196:199], v[110:113]
	v_mfma_f32_16x16x32_bf16 v[102:105], v[156:159], v[204:207], v[102:105]
	v_mfma_f32_16x16x32_bf16 v[94:97], v[164:167], v[204:207], v[94:97]
	v_mfma_f32_16x16x32_bf16 v[86:89], v[156:159], v[212:215], v[86:89]
	v_mfma_f32_16x16x32_bf16 v[78:81], v[164:167], v[212:215], v[78:81]
	v_mfma_f32_16x16x32_bf16 v[126:129], v[160:163], v[192:195], v[126:129]
	v_mfma_f32_16x16x32_bf16 v[122:125], v[168:171], v[192:195], v[122:125]
	v_mfma_f32_16x16x32_bf16 v[118:121], v[160:163], v[200:203], v[118:121]
	v_mfma_f32_16x16x32_bf16 v[110:113], v[168:171], v[200:203], v[110:113]
	v_mfma_f32_16x16x32_bf16 v[102:105], v[160:163], v[208:211], v[102:105]
	v_mfma_f32_16x16x32_bf16 v[94:97], v[168:171], v[208:211], v[94:97]
	v_mfma_f32_16x16x32_bf16 v[86:89], v[160:163], v[216:219], v[86:89]
	v_mfma_f32_16x16x32_bf16 v[78:81], v[168:171], v[216:219], v[78:81]
	s_setprio 0
	s_setprio 1
	v_mfma_f32_16x16x32_bf16 v[114:117], v[172:175], v[188:191], v[114:117]
	v_mfma_f32_16x16x32_bf16 v[106:109], v[180:183], v[188:191], v[106:109]
	v_mfma_f32_16x16x32_bf16 v[98:101], v[172:175], v[196:199], v[98:101]
	v_mfma_f32_16x16x32_bf16 v[90:93], v[180:183], v[196:199], v[90:93]
	v_mfma_f32_16x16x32_bf16 v[82:85], v[172:175], v[204:207], v[82:85]
	v_mfma_f32_16x16x32_bf16 v[74:77], v[180:183], v[204:207], v[74:77]
	v_mfma_f32_16x16x32_bf16 v[70:73], v[172:175], v[212:215], v[70:73]
	v_mfma_f32_16x16x32_bf16 v[66:69], v[180:183], v[212:215], v[66:69]
	v_mfma_f32_16x16x32_bf16 v[114:117], v[176:179], v[192:195], v[114:117]
	v_mfma_f32_16x16x32_bf16 v[106:109], v[184:187], v[192:195], v[106:109]
	v_mfma_f32_16x16x32_bf16 v[98:101], v[176:179], v[200:203], v[98:101]
	v_mfma_f32_16x16x32_bf16 v[90:93], v[184:187], v[200:203], v[90:93]
	v_mfma_f32_16x16x32_bf16 v[82:85], v[176:179], v[208:211], v[82:85]
	v_mfma_f32_16x16x32_bf16 v[74:77], v[184:187], v[208:211], v[74:77]
	v_mfma_f32_16x16x32_bf16 v[70:73], v[176:179], v[216:219], v[70:73]
	v_mfma_f32_16x16x32_bf16 v[66:69], v[184:187], v[216:219], v[66:69]
	s_setprio 0
	s_barrier
	s_add_i32 s59, s40, s28
	v_lshl_add_u64 v[146:147], s[24:25], 0, v[134:135]
	s_mov_b32 m0, s59
	ds_read_b128 v[188:191], v151 offset:16384
	ds_read_b128 v[192:195], v151 offset:17408
	ds_read_b128 v[196:199], v151 offset:18432
	ds_read_b128 v[200:203], v151 offset:19456
	ds_read_b128 v[204:207], v151 offset:20480
	ds_read_b128 v[208:211], v151 offset:21504
	ds_read_b128 v[212:215], v151 offset:22528
	ds_read_b128 v[216:219], v151 offset:23552
	global_load_lds_dwordx4 v[146:147], off
	s_add_i32 m0, s59, 0x2000
	s_add_u32 s60, s24, 0x80000
	v_lshl_add_u64 v[220:221], s[24:25], 0, v[130:131]
	s_addc_u32 s61, s25, 0
	s_add_i32 s59, s41, s28
	global_load_lds_dwordx4 v[220:221], off
	v_lshl_add_u64 v[222:223], s[60:61], 0, v[134:135]
	s_mov_b32 m0, s59
	v_lshl_add_u64 v[224:225], s[26:27], 0, v[132:133]
	global_load_lds_dwordx4 v[222:223], off
	v_lshl_add_u64 v[222:223], s[60:61], 0, v[130:131]
	s_add_i32 m0, s59, 0x2000
	s_nop 0
	global_load_lds_dwordx4 v[222:223], off
	v_lshl_add_u64 v[222:223], s[26:27], 0, v[136:137]
	s_mov_b32 m0, s21
	s_nop 0
	global_load_lds_dwordx4 v[222:223], off
	s_mov_b32 m0, s31
	s_nop 0
	global_load_lds_dwordx4 v[224:225], off
	s_waitcnt vmcnt(8)
	s_waitcnt lgkmcnt(0)
	s_setprio 1
	s_barrier
; #define PG8_STAGE(bufoff, gbase, voff) do { _Pragma("unroll") for (int _i = 0; _i < 2; ++_i) \
;         __builtin_amdgcn_global_load_lds((const unsigned*)((const char*)(gbase) + (voff)[_i]), (LAS unsigned*)(lds + (bufoff) + ldsw + _i * 8192), 16, 0, 0); } while (0)
; #define PG8_LDA(dst, b, h) do { _Pragma("unroll") for (int m = 0; m < 4; ++m) _Pragma("unroll") for (int k = 0; k < 2; ++k) dst[m][k] = *(const LAS bf16x8*)(lds + PG8_SA(b, h) + aoff + m * 2048 + k * 1024); } while (0)
; #define PG8_LDB(dst, b, h) do { _Pragma("unroll") for (int n = 0; n < 2; ++n) _Pragma("unroll") for (int k = 0; k < 2; ++k) dst[n][k] = *(const LAS bf16x8*)(lds + PG8_SB(b, h) + boff + n * 2048 + k * 1024); } while (0)
; #define PG8_MMA(ai, bj, At, Bt) do { __builtin_amdgcn_s_setprio(1); _Pragma("unroll") for (int m = 0; m < 4; ++m) _Pragma("unroll") for (int n = 0; n < 2; ++n) _Pragma("unroll") for (int k = 0; k < 2; ++k) \
;         acc[ai][bj][m][n] = __builtin_amdgcn_mfma_f32_16x16x32_bf16(Bt[n][k], At[m][k], acc[ai][bj][m][n], 0, 0, 0); __builtin_amdgcn_s_setprio(0); } while (0)
; #define PG8_WAIT_V(n) asm volatile("s_waitcnt vmcnt(" #n ")" ::: "memory")
; #define PG8_WAIT_L(n) asm volatile("s_waitcnt lgkmcnt(" #n ")" ::: "memory")
; #define PG8_BAR __builtin_amdgcn_s_barrier()
; #define PG8_SCHED __builtin_amdgcn_sched_barrier(0)
; template <class Epi, class Sched, bool ALIGN_EPI = false, bool SP2 = false>
; __device__ __forceinline__ void gemm_phase(LAS unsigned char* lds, const Gemm g, const Sched& S, const Epi& E) {
;     ...
;             PG8_WAIT_V(8); PG8_WAIT_L(0); PG8_BAR; PG8_MMA(1, 0, At, B0); PG8_MMA(1, 1, At, B1); PG8_BAR; PG8_SCHED;
;             PG8_LDB(B0, 1, 0); PG8_LDB(B1, 1, 1); PG8_SCHED; PG8_LDA(At, 1, 0); PG8_STAGE(PG8_SA(0, 1), a2 + hstepA, voffA);
;             PG8_WAIT_V(8); PG8_WAIT_L(0); PG8_BAR; PG8_MMA(0, 0, At, B0); PG8_MMA(0, 1, At, B1); PG8_BAR; PG8_SCHED;
	s_waitcnt lgkmcnt(0)
	v_mfma_f32_16x16x32_bf16 v[62:65], v[156:159], v[188:191], v[62:65]
	v_mfma_f32_16x16x32_bf16 v[58:61], v[164:167], v[188:191], v[58:61]
	v_mfma_f32_16x16x32_bf16 v[54:57], v[156:159], v[196:199], v[54:57]
	v_mfma_f32_16x16x32_bf16 v[46:49], v[164:167], v[196:199], v[46:49]
	v_mfma_f32_16x16x32_bf16 v[38:41], v[156:159], v[204:207], v[38:41]
	v_mfma_f32_16x16x32_bf16 v[30:33], v[164:167], v[204:207], v[30:33]
	v_mfma_f32_16x16x32_bf16 v[22:25], v[156:159], v[212:215], v[22:25]
	v_mfma_f32_16x16x32_bf16 v[14:17], v[164:167], v[212:215], v[14:17]
	v_mfma_f32_16x16x32_bf16 v[62:65], v[160:163], v[192:195], v[62:65]
	v_mfma_f32_16x16x32_bf16 v[58:61], v[168:171], v[192:195], v[58:61]
	v_mfma_f32_16x16x32_bf16 v[54:57], v[160:163], v[200:203], v[54:57]
	v_mfma_f32_16x16x32_bf16 v[46:49], v[168:171], v[200:203], v[46:49]
	v_mfma_f32_16x16x32_bf16 v[38:41], v[160:163], v[208:211], v[38:41]
	v_mfma_f32_16x16x32_bf16 v[30:33], v[168:171], v[208:211], v[30:33]
	v_mfma_f32_16x16x32_bf16 v[22:25], v[160:163], v[216:219], v[22:25]
	v_mfma_f32_16x16x32_bf16 v[14:17], v[168:171], v[216:219], v[14:17]
	s_setprio 0
	s_setprio 1
	v_mfma_f32_16x16x32_bf16 v[50:53], v[172:175], v[188:191], v[50:53]
	v_mfma_f32_16x16x32_bf16 v[42:45], v[180:183], v[188:191], v[42:45]
	v_mfma_f32_16x16x32_bf16 v[34:37], v[172:175], v[196:199], v[34:37]
	v_mfma_f32_16x16x32_bf16 v[26:29], v[180:183], v[196:199], v[26:29]
	v_mfma_f32_16x16x32_bf16 v[18:21], v[172:175], v[204:207], v[18:21]
	v_mfma_f32_16x16x32_bf16 v[10:13], v[180:183], v[204:207], v[10:13]
	v_mfma_f32_16x16x32_bf16 v[6:9], v[172:175], v[212:215], v[6:9]
	v_mfma_f32_16x16x32_bf16 v[2:5], v[180:183], v[212:215], v[2:5]
	v_mfma_f32_16x16x32_bf16 v[50:53], v[176:179], v[192:195], v[50:53]
	v_mfma_f32_16x16x32_bf16 v[42:45], v[184:187], v[192:195], v[42:45]
	v_mfma_f32_16x16x32_bf16 v[34:37], v[176:179], v[200:203], v[34:37]
	v_mfma_f32_16x16x32_bf16 v[26:29], v[184:187], v[200:203], v[26:29]
	v_mfma_f32_16x16x32_bf16 v[18:21], v[176:179], v[208:211], v[18:21]
	v_mfma_f32_16x16x32_bf16 v[10:13], v[184:187], v[208:211], v[10:13]
	v_mfma_f32_16x16x32_bf16 v[6:9], v[176:179], v[216:219], v[6:9]
	v_mfma_f32_16x16x32_bf16 v[2:5], v[184:187], v[216:219], v[2:5]
	s_setprio 0
	s_barrier
	ds_read_b128 v[156:159], v153
	ds_read_b128 v[160:163], v153 offset:1024
	ds_read_b128 v[164:167], v153 offset:2048
	ds_read_b128 v[168:171], v153 offset:3072
	ds_read_b128 v[172:175], v154
	ds_read_b128 v[176:179], v154 offset:1024
	ds_read_b128 v[180:183], v154 offset:2048
	ds_read_b128 v[184:187], v154 offset:3072
	s_add_u32 s26, s26, 0x80000
	s_addc_u32 s27, s27, 0
	s_mov_b32 m0, s33
	v_lshl_add_u64 v[226:227], s[26:27], 0, v[136:137]
	ds_read_b128 v[188:191], v151 offset:32768
	ds_read_b128 v[192:195], v151 offset:33792
	ds_read_b128 v[196:199], v151 offset:34816
	ds_read_b128 v[200:203], v151 offset:35840
	ds_read_b128 v[204:207], v151 offset:36864
	ds_read_b128 v[208:211], v151 offset:37888
	ds_read_b128 v[212:215], v151 offset:38912
	ds_read_b128 v[216:219], v151 offset:39936
	global_load_lds_dwordx4 v[226:227], off
	v_lshl_add_u64 v[226:227], s[26:27], 0, v[132:133]
	s_mov_b32 m0, s34
	s_nop 0
	global_load_lds_dwordx4 v[226:227], off
	s_waitcnt vmcnt(8)
	s_waitcnt lgkmcnt(0)
	s_setprio 1
	s_barrier
	s_waitcnt lgkmcnt(0)
	v_mfma_f32_16x16x32_bf16 v[126:129], v[156:159], v[188:191], v[126:129]
	v_mfma_f32_16x16x32_bf16 v[122:125], v[164:167], v[188:191], v[122:125]
	v_mfma_f32_16x16x32_bf16 v[118:121], v[156:159], v[196:199], v[118:121]
	v_mfma_f32_16x16x32_bf16 v[110:113], v[164:167], v[196:199], v[110:113]
	v_mfma_f32_16x16x32_bf16 v[102:105], v[156:159], v[204:207], v[102:105]
	v_mfma_f32_16x16x32_bf16 v[94:97], v[164:167], v[204:207], v[94:97]
	v_mfma_f32_16x16x32_bf16 v[86:89], v[156:159], v[212:215], v[86:89]
	v_mfma_f32_16x16x32_bf16 v[78:81], v[164:167], v[212:215], v[78:81]
	v_mfma_f32_16x16x32_bf16 v[126:129], v[160:163], v[192:195], v[126:129]
	v_mfma_f32_16x16x32_bf16 v[122:125], v[168:171], v[192:195], v[122:125]
	v_mfma_f32_16x16x32_bf16 v[118:121], v[160:163], v[200:203], v[118:121]
	v_mfma_f32_16x16x32_bf16 v[110:113], v[168:171], v[200:203], v[110:113]
	v_mfma_f32_16x16x32_bf16 v[102:105], v[160:163], v[208:211], v[102:105]
	v_mfma_f32_16x16x32_bf16 v[94:97], v[168:171], v[208:211], v[94:97]
	v_mfma_f32_16x16x32_bf16 v[86:89], v[160:163], v[216:219], v[86:89]
	v_mfma_f32_16x16x32_bf16 v[78:81], v[168:171], v[216:219], v[78:81]
	s_setprio 0
	s_setprio 1
	v_mfma_f32_16x16x32_bf16 v[114:117], v[172:175], v[188:191], v[114:117]
	v_mfma_f32_16x16x32_bf16 v[106:109], v[180:183], v[188:191], v[106:109]
	v_mfma_f32_16x16x32_bf16 v[98:101], v[172:175], v[196:199], v[98:101]
	v_mfma_f32_16x16x32_bf16 v[90:93], v[180:183], v[196:199], v[90:93]
	v_mfma_f32_16x16x32_bf16 v[82:85], v[172:175], v[204:207], v[82:85]
	v_mfma_f32_16x16x32_bf16 v[74:77], v[180:183], v[204:207], v[74:77]
	v_mfma_f32_16x16x32_bf16 v[70:73], v[172:175], v[212:215], v[70:73]
	v_mfma_f32_16x16x32_bf16 v[66:69], v[180:183], v[212:215], v[66:69]
	v_mfma_f32_16x16x32_bf16 v[114:117], v[176:179], v[192:195], v[114:117]
	v_mfma_f32_16x16x32_bf16 v[106:109], v[184:187], v[192:195], v[106:109]
	v_mfma_f32_16x16x32_bf16 v[98:101], v[176:179], v[200:203], v[98:101]
	v_mfma_f32_16x16x32_bf16 v[90:93], v[184:187], v[200:203], v[90:93]
	v_mfma_f32_16x16x32_bf16 v[82:85], v[176:179], v[208:211], v[82:85]
	v_mfma_f32_16x16x32_bf16 v[74:77], v[184:187], v[208:211], v[74:77]
	v_mfma_f32_16x16x32_bf16 v[70:73], v[176:179], v[216:219], v[70:73]
	v_mfma_f32_16x16x32_bf16 v[66:69], v[184:187], v[216:219], v[66:69]
	s_setprio 0
	s_barrier
; #define PG8_STAGE(bufoff, gbase, voff) do { _Pragma("unroll") for (int _i = 0; _i < 2; ++_i) \
;         __builtin_amdgcn_global_load_lds((const unsigned*)((const char*)(gbase) + (voff)[_i]), (LAS unsigned*)(lds + (bufoff) + ldsw + _i * 8192), 16, 0, 0); } while (0)
; #define PG8_LDA(dst, b, h) do { _Pragma("unroll") for (int m = 0; m < 4; ++m) _Pragma("unroll") for (int k = 0; k < 2; ++k) dst[m][k] = *(const LAS bf16x8*)(lds + PG8_SA(b, h) + aoff + m * 2048 + k * 1024); } while (0)
; #define PG8_MMA(ai, bj, At, Bt) do { __builtin_amdgcn_s_setprio(1); _Pragma("unroll") for (int m = 0; m < 4; ++m) _Pragma("unroll") for (int n = 0; n < 2; ++n) _Pragma("unroll") for (int k = 0; k < 2; ++k) \
;         acc[ai][bj][m][n] = __builtin_amdgcn_mfma_f32_16x16x32_bf16(Bt[n][k], At[m][k], acc[ai][bj][m][n], 0, 0, 0); __builtin_amdgcn_s_setprio(0); } while (0)
; #define PG8_WAIT_V(n) asm volatile("s_waitcnt vmcnt(" #n ")" ::: "memory")
; #define PG8_WAIT_L(n) asm volatile("s_waitcnt lgkmcnt(" #n ")" ::: "memory")
; #define PG8_BAR __builtin_amdgcn_s_barrier()
; #define PG8_SCHED __builtin_amdgcn_sched_barrier(0)
; template <class Epi, class Sched, bool ALIGN_EPI = false, bool SP2 = false>
; __device__ __forceinline__ void gemm_phase(LAS unsigned char* lds, const Gemm g, const Sched& S, const Epi& E) {
;     ...
;         for (int t = 0; t < nt; t += 2) {
;             const bool last = (t == nt - 2);
;     ...
;             PG8_LDA(At, 1, 1); PG8_STAGE(PG8_SB(1, 0), b3, voffB); PG8_STAGE(PG8_SB(1, 1), b3 + hstepB, voffB); PG8_STAGE(PG8_SA(1, 0), a3, voffA);
;             PG8_WAIT_V(8); PG8_WAIT_L(0); PG8_BAR; PG8_MMA(1, 0, At, B0); PG8_MMA(1, 1, At, B1); PG8_BAR; PG8_SCHED;
	s_add_i32 s26, s44, s28
	v_lshl_add_u64 v[146:147], v[146:147], 0, s[6:7]
	s_mov_b32 m0, s26
	ds_read_b128 v[188:191], v151 offset:49152
	ds_read_b128 v[192:195], v151 offset:50176
	ds_read_b128 v[196:199], v151 offset:51200
	ds_read_b128 v[200:203], v151 offset:52224
	ds_read_b128 v[204:207], v151 offset:53248
	ds_read_b128 v[208:211], v151 offset:54272
	ds_read_b128 v[212:215], v151 offset:55296
	ds_read_b128 v[216:219], v151 offset:56320
	global_load_lds_dwordx4 v[146:147], off
	s_add_i32 m0, s26, 0x2000
	s_add_u32 s24, s24, 0x80080
	v_lshl_add_u64 v[146:147], v[220:221], 0, s[6:7]
	s_addc_u32 s25, s25, 0
	s_add_i32 s26, s45, s28
	global_load_lds_dwordx4 v[146:147], off
	v_lshl_add_u64 v[146:147], s[24:25], 0, v[134:135]
	s_mov_b32 m0, s26
	s_nop 0
	global_load_lds_dwordx4 v[146:147], off
	v_lshl_add_u64 v[146:147], s[24:25], 0, v[130:131]
	s_add_i32 m0, s26, 0x2000
	s_nop 0
	global_load_lds_dwordx4 v[146:147], off
	v_lshl_add_u64 v[146:147], v[222:223], 0, s[6:7]
	s_mov_b32 m0, s36
	s_nop 0
	global_load_lds_dwordx4 v[146:147], off
	v_lshl_add_u64 v[146:147], v[224:225], 0, s[6:7]
	s_mov_b32 m0, s37
	s_nop 0
	global_load_lds_dwordx4 v[146:147], off
	s_waitcnt vmcnt(8)
	s_waitcnt lgkmcnt(0)
	s_setprio 1
	s_barrier
	s_waitcnt lgkmcnt(0)
	v_mfma_f32_16x16x32_bf16 v[62:65], v[156:159], v[188:191], v[62:65]
	v_mfma_f32_16x16x32_bf16 v[58:61], v[164:167], v[188:191], v[58:61]
	v_mfma_f32_16x16x32_bf16 v[54:57], v[156:159], v[196:199], v[54:57]
	v_mfma_f32_16x16x32_bf16 v[46:49], v[164:167], v[196:199], v[46:49]
	v_mfma_f32_16x16x32_bf16 v[38:41], v[156:159], v[204:207], v[38:41]
	v_mfma_f32_16x16x32_bf16 v[30:33], v[164:167], v[204:207], v[30:33]
	v_mfma_f32_16x16x32_bf16 v[22:25], v[156:159], v[212:215], v[22:25]
	v_mfma_f32_16x16x32_bf16 v[14:17], v[164:167], v[212:215], v[14:17]
	v_mfma_f32_16x16x32_bf16 v[62:65], v[160:163], v[192:195], v[62:65]
	v_mfma_f32_16x16x32_bf16 v[58:61], v[168:171], v[192:195], v[58:61]
	v_mfma_f32_16x16x32_bf16 v[54:57], v[160:163], v[200:203], v[54:57]
	v_mfma_f32_16x16x32_bf16 v[46:49], v[168:171], v[200:203], v[46:49]
	v_mfma_f32_16x16x32_bf16 v[38:41], v[160:163], v[208:211], v[38:41]
	v_mfma_f32_16x16x32_bf16 v[30:33], v[168:171], v[208:211], v[30:33]
	v_mfma_f32_16x16x32_bf16 v[22:25], v[160:163], v[216:219], v[22:25]
	v_mfma_f32_16x16x32_bf16 v[14:17], v[168:171], v[216:219], v[14:17]
	s_setprio 0
	s_setprio 1
	v_mfma_f32_16x16x32_bf16 v[50:53], v[172:175], v[188:191], v[50:53]
	v_mfma_f32_16x16x32_bf16 v[42:45], v[180:183], v[188:191], v[42:45]
	v_mfma_f32_16x16x32_bf16 v[34:37], v[172:175], v[196:199], v[34:37]
	v_mfma_f32_16x16x32_bf16 v[26:29], v[180:183], v[196:199], v[26:29]
	v_mfma_f32_16x16x32_bf16 v[18:21], v[172:175], v[204:207], v[18:21]
	v_mfma_f32_16x16x32_bf16 v[10:13], v[180:183], v[204:207], v[10:13]
	v_mfma_f32_16x16x32_bf16 v[6:9], v[172:175], v[212:215], v[6:9]
	v_mfma_f32_16x16x32_bf16 v[2:5], v[180:183], v[212:215], v[2:5]
	v_mfma_f32_16x16x32_bf16 v[50:53], v[176:179], v[192:195], v[50:53]
	v_mfma_f32_16x16x32_bf16 v[42:45], v[184:187], v[192:195], v[42:45]
	v_mfma_f32_16x16x32_bf16 v[34:37], v[176:179], v[200:203], v[34:37]
	v_mfma_f32_16x16x32_bf16 v[26:29], v[184:187], v[200:203], v[26:29]
	v_mfma_f32_16x16x32_bf16 v[18:21], v[176:179], v[208:211], v[18:21]
	v_mfma_f32_16x16x32_bf16 v[10:13], v[184:187], v[208:211], v[10:13]
	v_mfma_f32_16x16x32_bf16 v[6:9], v[176:179], v[216:219], v[6:9]
	v_mfma_f32_16x16x32_bf16 v[2:5], v[184:187], v[216:219], v[2:5]
	s_setprio 0
	s_barrier
	s_add_i32 s58, s58, 2
	s_add_u32 s22, s22, 0x100
	s_addc_u32 s23, s23, 0
	s_add_u32 s51, s51, 0x100
	s_addc_u32 s55, s55, 0
	s_cmp_gt_u32 s58, 29
	s_cbranch_scc0 .LBB0_349
	s_and_b64 vcc, exec, s[10:11]
	s_cbranch_vccz .LBB0_352
	s_barrier

; #define PG8_STAGE(bufoff, gbase, voff) do { _Pragma("unroll") for (int _i = 0; _i < 2; ++_i) \
;         __builtin_amdgcn_global_load_lds((const unsigned*)((const char*)(gbase) + (voff)[_i]), (LAS unsigned*)(lds + (bufoff) + ldsw + _i * 8192), 16, 0, 0); } while (0)
; #define PG8_LDA(dst, b, h) do { _Pragma("unroll") for (int m = 0; m < 4; ++m) _Pragma("unroll") for (int k = 0; k < 2; ++k) dst[m][k] = *(const LAS bf16x8*)(lds + PG8_SA(b, h) + aoff + m * 2048 + k * 1024); } while (0)
; #define PG8_LDB(dst, b, h) do { _Pragma("unroll") for (int n = 0; n < 2; ++n) _Pragma("unroll") for (int k = 0; k < 2; ++k) dst[n][k] = *(const LAS bf16x8*)(lds + PG8_SB(b, h) + boff + n * 2048 + k * 1024); } while (0)
; #define PG8_MMA(ai, bj, At, Bt) do { __builtin_amdgcn_s_setprio(1); _Pragma("unroll") for (int m = 0; m < 4; ++m) _Pragma("unroll") for (int n = 0; n < 2; ++n) _Pragma("unroll") for (int k = 0; k < 2; ++k) \
;         acc[ai][bj][m][n] = __builtin_amdgcn_mfma_f32_16x16x32_bf16(Bt[n][k], At[m][k], acc[ai][bj][m][n], 0, 0, 0); __builtin_amdgcn_s_setprio(0); } while (0)
; #define PG8_WAIT_V(n) asm volatile("s_waitcnt vmcnt(" #n ")" ::: "memory")
; #define PG8_WAIT_L(n) asm volatile("s_waitcnt lgkmcnt(" #n ")" ::: "memory")
; #define PG8_BAR __builtin_amdgcn_s_barrier()
; #define PG8_SCHED __builtin_amdgcn_sched_barrier(0)
; template <class Epi, class Sched, bool ALIGN_EPI = false, bool SP2 = false>
; __device__ __forceinline__ void gemm_phase(LAS unsigned char* lds, const Gemm g, const Sched& S, const Epi& E) {
;     ...
;             const bool last = (t == nt - 2);
;             const char* a1 = cA + (size_t)(t + 1) * kstep;
;             const char* a2 = last ? nA : cA + (size_t)(t + 2) * kstep; const char* b2 = last ? nB : cB + (size_t)(t + 2) * kstep;
;             const char* a3 = a2 + kstep; const char* b3 = b2 + kstep;
;             if (last && has_next) S.a_ready(nxt);
;             if constexpr (SP2) {
;             PG8_LDB(B0, 0, 0); PG8_LDB(B1, 0, 1); PG8_SCHED; PG8_LDA(At, 0, 0); PG8_STAGE(PG8_SA(1, 1), a1 + hstepA, voffA);
;             PG8_WAIT_V(8); PG8_WAIT_L(0); PG8_BAR; PG8_MMA(0, 0, At, B0); PG8_MMA(0, 1, At, B1); PG8_BAR; PG8_SCHED;
;             PG8_LDA(At, 0, 1); PG8_STAGE(PG8_SB(0, 0), b2, voffB); PG8_STAGE(PG8_SB(0, 1), b2 + hstepB, voffB); PG8_STAGE(PG8_SA(0, 0), a2, voffA);
.LBB0_560:
	s_add_u32 s27, s20, s26
	s_addc_u32 s34, s21, 0
	s_add_u32 s30, s27, 0x100
	s_addc_u32 s31, s34, 0
	s_and_b64 s[28:29], s[24:25], exec
	s_cselect_b32 s29, s1, s31
	s_cselect_b32 s28, s0, s30
	s_add_u32 s26, s16, s26
	s_addc_u32 s30, s17, 0
	s_add_u32 s26, s26, 0x100
	s_addc_u32 s30, s30, 0
	s_and_b64 s[24:25], s[24:25], exec
	s_cselect_b32 s31, s19, s30
	s_cselect_b32 s30, s18, s26
	s_add_u32 s36, s27, 0x18080
	ds_read_b128 v[154:157], v147
	ds_read_b128 v[158:161], v147 offset:1024
	ds_read_b128 v[162:165], v147 offset:2048
	ds_read_b128 v[166:169], v147 offset:3072
	ds_read_b128 v[170:173], v148
	ds_read_b128 v[174:177], v148 offset:1024
	ds_read_b128 v[178:181], v148 offset:2048
	ds_read_b128 v[182:185], v148 offset:3072
	s_addc_u32 s37, s34, 0
	s_add_i32 s73, s54, s39
	s_add_i32 m0, s40, 0xc000
	s_add_i32 s76, s40, 0xe000
	s_add_i32 s70, s73, 0x2000
	s_add_u32 s34, s30, 0x18000
	s_addc_u32 s35, s31, 0
	s_add_i32 s72, s55, s39
	s_add_i32 s71, s72, 0x2000
	s_add_u32 s26, s28, 0x18000
	s_addc_u32 s27, s29, 0
	s_add_i32 s67, s57, s39
	s_add_i32 s65, s67, 0x2000
	s_add_u32 s24, s30, 0x18080
	s_addc_u32 s25, s31, 0
	s_add_i32 s66, s58, s39
	s_add_i32 s63, s66, 0x2000
	v_lshl_add_u64 v[218:219], s[36:37], 0, v[130:131]
	ds_read_b128 v[186:189], v149
	ds_read_b128 v[190:193], v149 offset:1024
	ds_read_b128 v[194:197], v149 offset:2048
	ds_read_b128 v[198:201], v149 offset:3072
	ds_read_b128 v[202:205], v149 offset:4096
	ds_read_b128 v[206:209], v149 offset:5120
	ds_read_b128 v[210:213], v149 offset:6144
	ds_read_b128 v[214:217], v149 offset:7168
	global_load_lds_dwordx4 v[218:219], off
	v_lshl_add_u64 v[218:219], s[36:37], 0, v[134:135]
	s_mov_b32 m0, s76
	s_nop 0
	global_load_lds_dwordx4 v[218:219], off
	s_waitcnt vmcnt(8)
	s_waitcnt lgkmcnt(0)
	s_setprio 1
	s_barrier
	s_waitcnt lgkmcnt(0)
	v_mfma_f32_16x16x32_bf16 v[126:129], v[154:157], v[186:189], v[126:129]
	v_mfma_f32_16x16x32_bf16 v[122:125], v[162:165], v[186:189], v[122:125]
	v_mfma_f32_16x16x32_bf16 v[118:121], v[154:157], v[194:197], v[118:121]
	v_mfma_f32_16x16x32_bf16 v[110:113], v[162:165], v[194:197], v[110:113]
	v_mfma_f32_16x16x32_bf16 v[102:105], v[154:157], v[202:205], v[102:105]
	v_mfma_f32_16x16x32_bf16 v[94:97], v[162:165], v[202:205], v[94:97]
	v_mfma_f32_16x16x32_bf16 v[86:89], v[154:157], v[210:213], v[86:89]
	v_mfma_f32_16x16x32_bf16 v[78:81], v[162:165], v[210:213], v[78:81]
	v_mfma_f32_16x16x32_bf16 v[126:129], v[158:161], v[190:193], v[126:129]
	v_mfma_f32_16x16x32_bf16 v[122:125], v[166:169], v[190:193], v[122:125]
	v_mfma_f32_16x16x32_bf16 v[118:121], v[158:161], v[198:201], v[118:121]
	v_mfma_f32_16x16x32_bf16 v[110:113], v[166:169], v[198:201], v[110:113]
	v_mfma_f32_16x16x32_bf16 v[102:105], v[158:161], v[206:209], v[102:105]
	v_mfma_f32_16x16x32_bf16 v[94:97], v[166:169], v[206:209], v[94:97]
	v_mfma_f32_16x16x32_bf16 v[86:89], v[158:161], v[214:217], v[86:89]
	v_mfma_f32_16x16x32_bf16 v[78:81], v[166:169], v[214:217], v[78:81]
	s_setprio 0
	s_setprio 1
	v_mfma_f32_16x16x32_bf16 v[114:117], v[170:173], v[186:189], v[114:117]
	v_mfma_f32_16x16x32_bf16 v[106:109], v[178:181], v[186:189], v[106:109]
	v_mfma_f32_16x16x32_bf16 v[98:101], v[170:173], v[194:197], v[98:101]
	v_mfma_f32_16x16x32_bf16 v[90:93], v[178:181], v[194:197], v[90:93]
	v_mfma_f32_16x16x32_bf16 v[82:85], v[170:173], v[202:205], v[82:85]
	v_mfma_f32_16x16x32_bf16 v[74:77], v[178:181], v[202:205], v[74:77]
	v_mfma_f32_16x16x32_bf16 v[70:73], v[170:173], v[210:213], v[70:73]
	v_mfma_f32_16x16x32_bf16 v[66:69], v[178:181], v[210:213], v[66:69]
	v_mfma_f32_16x16x32_bf16 v[114:117], v[174:177], v[190:193], v[114:117]
	v_mfma_f32_16x16x32_bf16 v[106:109], v[182:185], v[190:193], v[106:109]
	v_mfma_f32_16x16x32_bf16 v[98:101], v[174:177], v[198:201], v[98:101]
	v_mfma_f32_16x16x32_bf16 v[90:93], v[182:185], v[198:201], v[90:93]
	v_mfma_f32_16x16x32_bf16 v[82:85], v[174:177], v[206:209], v[82:85]
	v_mfma_f32_16x16x32_bf16 v[74:77], v[182:185], v[206:209], v[74:77]
	v_mfma_f32_16x16x32_bf16 v[70:73], v[174:177], v[214:217], v[70:73]
	v_mfma_f32_16x16x32_bf16 v[66:69], v[182:185], v[214:217], v[66:69]
	s_setprio 0
	s_barrier
	s_mov_b32 m0, s73
	v_lshl_add_u64 v[218:219], s[30:31], 0, v[132:133]
	ds_read_b128 v[186:189], v149 offset:16384
	ds_read_b128 v[190:193], v149 offset:17408
	ds_read_b128 v[194:197], v149 offset:18432
	ds_read_b128 v[198:201], v149 offset:19456
	ds_read_b128 v[202:205], v149 offset:20480
	ds_read_b128 v[206:209], v149 offset:21504
	ds_read_b128 v[210:213], v149 offset:22528
	ds_read_b128 v[214:217], v149 offset:23552
	global_load_lds_dwordx4 v[218:219], off
	v_lshl_add_u64 v[220:221], s[30:31], 0, v[136:137]
	s_mov_b32 m0, s70
	v_lshl_add_u64 v[222:223], s[34:35], 0, v[132:133]
	global_load_lds_dwordx4 v[220:221], off
	s_mov_b32 m0, s72
	v_lshl_add_u64 v[224:225], s[28:29], 0, v[134:135]
	global_load_lds_dwordx4 v[222:223], off
	v_lshl_add_u64 v[222:223], s[34:35], 0, v[136:137]
	s_mov_b32 m0, s71
	s_nop 0
	global_load_lds_dwordx4 v[222:223], off
	v_lshl_add_u64 v[222:223], s[28:29], 0, v[130:131]
	s_mov_b32 m0, s40
	s_nop 0
	global_load_lds_dwordx4 v[222:223], off
	s_mov_b32 m0, s33
	s_nop 0
	global_load_lds_dwordx4 v[224:225], off
	s_waitcnt vmcnt(8)
	s_waitcnt lgkmcnt(0)
	s_setprio 1
	s_barrier
; #define PG8_STAGE(bufoff, gbase, voff) do { _Pragma("unroll") for (int _i = 0; _i < 2; ++_i) \
;         __builtin_amdgcn_global_load_lds((const unsigned*)((const char*)(gbase) + (voff)[_i]), (LAS unsigned*)(lds + (bufoff) + ldsw + _i * 8192), 16, 0, 0); } while (0)
; #define PG8_LDA(dst, b, h) do { _Pragma("unroll") for (int m = 0; m < 4; ++m) _Pragma("unroll") for (int k = 0; k < 2; ++k) dst[m][k] = *(const LAS bf16x8*)(lds + PG8_SA(b, h) + aoff + m * 2048 + k * 1024); } while (0)
; #define PG8_LDB(dst, b, h) do { _Pragma("unroll") for (int n = 0; n < 2; ++n) _Pragma("unroll") for (int k = 0; k < 2; ++k) dst[n][k] = *(const LAS bf16x8*)(lds + PG8_SB(b, h) + boff + n * 2048 + k * 1024); } while (0)
; #define PG8_MMA(ai, bj, At, Bt) do { __builtin_amdgcn_s_setprio(1); _Pragma("unroll") for (int m = 0; m < 4; ++m) _Pragma("unroll") for (int n = 0; n < 2; ++n) _Pragma("unroll") for (int k = 0; k < 2; ++k) \
;         acc[ai][bj][m][n] = __builtin_amdgcn_mfma_f32_16x16x32_bf16(Bt[n][k], At[m][k], acc[ai][bj][m][n], 0, 0, 0); __builtin_amdgcn_s_setprio(0); } while (0)
; #define PG8_WAIT_V(n) asm volatile("s_waitcnt vmcnt(" #n ")" ::: "memory")
; #define PG8_WAIT_L(n) asm volatile("s_waitcnt lgkmcnt(" #n ")" ::: "memory")
; #define PG8_BAR __builtin_amdgcn_s_barrier()
; #define PG8_SCHED __builtin_amdgcn_sched_barrier(0)
; template <class Epi, class Sched, bool ALIGN_EPI = false, bool SP2 = false>
; __device__ __forceinline__ void gemm_phase(LAS unsigned char* lds, const Gemm g, const Sched& S, const Epi& E) {
;     ...
;             PG8_WAIT_V(8); PG8_WAIT_L(0); PG8_BAR; PG8_MMA(1, 0, At, B0); PG8_MMA(1, 1, At, B1); PG8_BAR; PG8_SCHED;
;             PG8_LDB(B0, 1, 0); PG8_LDB(B1, 1, 1); PG8_SCHED; PG8_LDA(At, 1, 0); PG8_STAGE(PG8_SA(0, 1), a2 + hstepA, voffA);
;             PG8_WAIT_V(8); PG8_WAIT_L(0); PG8_BAR; PG8_MMA(0, 0, At, B0); PG8_MMA(0, 1, At, B1); PG8_BAR; PG8_SCHED;
	s_waitcnt lgkmcnt(0)
	v_mfma_f32_16x16x32_bf16 v[62:65], v[154:157], v[186:189], v[62:65]
	v_mfma_f32_16x16x32_bf16 v[58:61], v[162:165], v[186:189], v[58:61]
	v_mfma_f32_16x16x32_bf16 v[54:57], v[154:157], v[194:197], v[54:57]
	v_mfma_f32_16x16x32_bf16 v[46:49], v[162:165], v[194:197], v[46:49]
	v_mfma_f32_16x16x32_bf16 v[38:41], v[154:157], v[202:205], v[38:41]
	v_mfma_f32_16x16x32_bf16 v[30:33], v[162:165], v[202:205], v[30:33]
	v_mfma_f32_16x16x32_bf16 v[22:25], v[154:157], v[210:213], v[22:25]
	v_mfma_f32_16x16x32_bf16 v[14:17], v[162:165], v[210:213], v[14:17]
	v_mfma_f32_16x16x32_bf16 v[62:65], v[158:161], v[190:193], v[62:65]
	v_mfma_f32_16x16x32_bf16 v[58:61], v[166:169], v[190:193], v[58:61]
	v_mfma_f32_16x16x32_bf16 v[54:57], v[158:161], v[198:201], v[54:57]
	v_mfma_f32_16x16x32_bf16 v[46:49], v[166:169], v[198:201], v[46:49]
	v_mfma_f32_16x16x32_bf16 v[38:41], v[158:161], v[206:209], v[38:41]
	v_mfma_f32_16x16x32_bf16 v[30:33], v[166:169], v[206:209], v[30:33]
	v_mfma_f32_16x16x32_bf16 v[22:25], v[158:161], v[214:217], v[22:25]
	v_mfma_f32_16x16x32_bf16 v[14:17], v[166:169], v[214:217], v[14:17]
	s_setprio 0
	s_setprio 1
	v_mfma_f32_16x16x32_bf16 v[50:53], v[170:173], v[186:189], v[50:53]
	v_mfma_f32_16x16x32_bf16 v[42:45], v[178:181], v[186:189], v[42:45]
	v_mfma_f32_16x16x32_bf16 v[34:37], v[170:173], v[194:197], v[34:37]
	v_mfma_f32_16x16x32_bf16 v[26:29], v[178:181], v[194:197], v[26:29]
	v_mfma_f32_16x16x32_bf16 v[18:21], v[170:173], v[202:205], v[18:21]
	v_mfma_f32_16x16x32_bf16 v[10:13], v[178:181], v[202:205], v[10:13]
	v_mfma_f32_16x16x32_bf16 v[6:9], v[170:173], v[210:213], v[6:9]
	v_mfma_f32_16x16x32_bf16 v[2:5], v[178:181], v[210:213], v[2:5]
	v_mfma_f32_16x16x32_bf16 v[50:53], v[174:177], v[190:193], v[50:53]
	v_mfma_f32_16x16x32_bf16 v[42:45], v[182:185], v[190:193], v[42:45]
	v_mfma_f32_16x16x32_bf16 v[34:37], v[174:177], v[198:201], v[34:37]
	v_mfma_f32_16x16x32_bf16 v[26:29], v[182:185], v[198:201], v[26:29]
	v_mfma_f32_16x16x32_bf16 v[18:21], v[174:177], v[206:209], v[18:21]
	v_mfma_f32_16x16x32_bf16 v[10:13], v[182:185], v[206:209], v[10:13]
	v_mfma_f32_16x16x32_bf16 v[6:9], v[174:177], v[214:217], v[6:9]
	v_mfma_f32_16x16x32_bf16 v[2:5], v[182:185], v[214:217], v[2:5]
	s_setprio 0
	s_barrier
	ds_read_b128 v[154:157], v150
	ds_read_b128 v[158:161], v150 offset:1024
	ds_read_b128 v[162:165], v150 offset:2048
	ds_read_b128 v[166:169], v150 offset:3072
	ds_read_b128 v[170:173], v151
	ds_read_b128 v[174:177], v151 offset:1024
	ds_read_b128 v[178:181], v151 offset:2048
	ds_read_b128 v[182:185], v151 offset:3072
	s_mov_b32 m0, s41
	v_lshl_add_u64 v[226:227], s[26:27], 0, v[130:131]
	ds_read_b128 v[186:189], v149 offset:32768
	ds_read_b128 v[190:193], v149 offset:33792
	ds_read_b128 v[194:197], v149 offset:34816
	ds_read_b128 v[198:201], v149 offset:35840
	ds_read_b128 v[202:205], v149 offset:36864
	ds_read_b128 v[206:209], v149 offset:37888
	ds_read_b128 v[210:213], v149 offset:38912
	ds_read_b128 v[214:217], v149 offset:39936
	global_load_lds_dwordx4 v[226:227], off
	v_lshl_add_u64 v[226:227], s[26:27], 0, v[134:135]
	s_mov_b32 m0, s44
	s_nop 0
	global_load_lds_dwordx4 v[226:227], off
	s_waitcnt vmcnt(8)
	s_waitcnt lgkmcnt(0)
	s_setprio 1
	s_barrier
	s_waitcnt lgkmcnt(0)
	v_mfma_f32_16x16x32_bf16 v[126:129], v[154:157], v[186:189], v[126:129]
	v_mfma_f32_16x16x32_bf16 v[122:125], v[162:165], v[186:189], v[122:125]
	v_mfma_f32_16x16x32_bf16 v[118:121], v[154:157], v[194:197], v[118:121]
	v_mfma_f32_16x16x32_bf16 v[110:113], v[162:165], v[194:197], v[110:113]
	v_mfma_f32_16x16x32_bf16 v[102:105], v[154:157], v[202:205], v[102:105]
	v_mfma_f32_16x16x32_bf16 v[94:97], v[162:165], v[202:205], v[94:97]
	v_mfma_f32_16x16x32_bf16 v[86:89], v[154:157], v[210:213], v[86:89]
	v_mfma_f32_16x16x32_bf16 v[78:81], v[162:165], v[210:213], v[78:81]
	v_mfma_f32_16x16x32_bf16 v[126:129], v[158:161], v[190:193], v[126:129]
	v_mfma_f32_16x16x32_bf16 v[122:125], v[166:169], v[190:193], v[122:125]
	v_mfma_f32_16x16x32_bf16 v[118:121], v[158:161], v[198:201], v[118:121]
	v_mfma_f32_16x16x32_bf16 v[110:113], v[166:169], v[198:201], v[110:113]
	v_mfma_f32_16x16x32_bf16 v[102:105], v[158:161], v[206:209], v[102:105]
	v_mfma_f32_16x16x32_bf16 v[94:97], v[166:169], v[206:209], v[94:97]
	v_mfma_f32_16x16x32_bf16 v[86:89], v[158:161], v[214:217], v[86:89]
	v_mfma_f32_16x16x32_bf16 v[78:81], v[166:169], v[214:217], v[78:81]
	s_setprio 0
	s_setprio 1
	v_mfma_f32_16x16x32_bf16 v[114:117], v[170:173], v[186:189], v[114:117]
	v_mfma_f32_16x16x32_bf16 v[106:109], v[178:181], v[186:189], v[106:109]
	v_mfma_f32_16x16x32_bf16 v[98:101], v[170:173], v[194:197], v[98:101]
	v_mfma_f32_16x16x32_bf16 v[90:93], v[178:181], v[194:197], v[90:93]
	v_mfma_f32_16x16x32_bf16 v[82:85], v[170:173], v[202:205], v[82:85]
	v_mfma_f32_16x16x32_bf16 v[74:77], v[178:181], v[202:205], v[74:77]
	v_mfma_f32_16x16x32_bf16 v[70:73], v[170:173], v[210:213], v[70:73]
	v_mfma_f32_16x16x32_bf16 v[66:69], v[178:181], v[210:213], v[66:69]
	v_mfma_f32_16x16x32_bf16 v[114:117], v[174:177], v[190:193], v[114:117]
	v_mfma_f32_16x16x32_bf16 v[106:109], v[182:185], v[190:193], v[106:109]
	v_mfma_f32_16x16x32_bf16 v[98:101], v[174:177], v[198:201], v[98:101]
	v_mfma_f32_16x16x32_bf16 v[90:93], v[182:185], v[198:201], v[90:93]
	v_mfma_f32_16x16x32_bf16 v[82:85], v[174:177], v[206:209], v[82:85]
	v_mfma_f32_16x16x32_bf16 v[74:77], v[182:185], v[206:209], v[74:77]
	v_mfma_f32_16x16x32_bf16 v[70:73], v[174:177], v[214:217], v[70:73]
	v_mfma_f32_16x16x32_bf16 v[66:69], v[182:185], v[214:217], v[66:69]
	s_setprio 0
	s_barrier
; #define PG8_STAGE(bufoff, gbase, voff) do { _Pragma("unroll") for (int _i = 0; _i < 2; ++_i) \
;         __builtin_amdgcn_global_load_lds((const unsigned*)((const char*)(gbase) + (voff)[_i]), (LAS unsigned*)(lds + (bufoff) + ldsw + _i * 8192), 16, 0, 0); } while (0)
; #define PG8_LDA(dst, b, h) do { _Pragma("unroll") for (int m = 0; m < 4; ++m) _Pragma("unroll") for (int k = 0; k < 2; ++k) dst[m][k] = *(const LAS bf16x8*)(lds + PG8_SA(b, h) + aoff + m * 2048 + k * 1024); } while (0)
; #define PG8_MMA(ai, bj, At, Bt) do { __builtin_amdgcn_s_setprio(1); _Pragma("unroll") for (int m = 0; m < 4; ++m) _Pragma("unroll") for (int n = 0; n < 2; ++n) _Pragma("unroll") for (int k = 0; k < 2; ++k) \
;         acc[ai][bj][m][n] = __builtin_amdgcn_mfma_f32_16x16x32_bf16(Bt[n][k], At[m][k], acc[ai][bj][m][n], 0, 0, 0); __builtin_amdgcn_s_setprio(0); } while (0)
; #define PG8_WAIT_V(n) asm volatile("s_waitcnt vmcnt(" #n ")" ::: "memory")
; #define PG8_WAIT_L(n) asm volatile("s_waitcnt lgkmcnt(" #n ")" ::: "memory")
; #define PG8_BAR __builtin_amdgcn_s_barrier()
; #define PG8_SCHED __builtin_amdgcn_sched_barrier(0)
; template <class Epi, class Sched, bool ALIGN_EPI = false, bool SP2 = false>
; __device__ __forceinline__ void gemm_phase(LAS unsigned char* lds, const Gemm g, const Sched& S, const Epi& E) {
;     ...
;             PG8_LDA(At, 1, 1); PG8_STAGE(PG8_SB(1, 0), b3, voffB); PG8_STAGE(PG8_SB(1, 1), b3 + hstepB, voffB); PG8_STAGE(PG8_SA(1, 0), a3, voffA);
;             PG8_WAIT_V(8); PG8_WAIT_L(0); PG8_BAR; PG8_MMA(1, 0, At, B0); PG8_MMA(1, 1, At, B1); PG8_BAR; PG8_SCHED;
	s_mov_b32 m0, s67
	v_lshl_add_u64 v[218:219], v[218:219], 0, s[12:13]
	ds_read_b128 v[186:189], v149 offset:49152
	ds_read_b128 v[190:193], v149 offset:50176
	ds_read_b128 v[194:197], v149 offset:51200
	ds_read_b128 v[198:201], v149 offset:52224
	ds_read_b128 v[202:205], v149 offset:53248
	ds_read_b128 v[206:209], v149 offset:54272
	ds_read_b128 v[210:213], v149 offset:55296
	ds_read_b128 v[214:217], v149 offset:56320
	global_load_lds_dwordx4 v[218:219], off
	v_lshl_add_u64 v[218:219], v[220:221], 0, s[12:13]
	s_mov_b32 m0, s65
	s_nop 0
	global_load_lds_dwordx4 v[218:219], off
	v_lshl_add_u64 v[218:219], s[24:25], 0, v[132:133]
	s_mov_b32 m0, s66
	s_nop 0
	global_load_lds_dwordx4 v[218:219], off
	v_lshl_add_u64 v[218:219], s[24:25], 0, v[136:137]
	s_mov_b32 m0, s63
	s_nop 0
	global_load_lds_dwordx4 v[218:219], off
	v_lshl_add_u64 v[218:219], v[222:223], 0, s[12:13]
	s_mov_b32 m0, s45
	s_nop 0
	global_load_lds_dwordx4 v[218:219], off
	v_lshl_add_u64 v[218:219], v[224:225], 0, s[12:13]
	s_mov_b32 m0, s46
	s_nop 0
	global_load_lds_dwordx4 v[218:219], off
	s_waitcnt vmcnt(8)
	s_waitcnt lgkmcnt(0)
	s_setprio 1
	s_barrier
	s_waitcnt lgkmcnt(0)
	v_mfma_f32_16x16x32_bf16 v[62:65], v[154:157], v[186:189], v[62:65]
	v_mfma_f32_16x16x32_bf16 v[58:61], v[162:165], v[186:189], v[58:61]
	v_mfma_f32_16x16x32_bf16 v[54:57], v[154:157], v[194:197], v[54:57]
	v_mfma_f32_16x16x32_bf16 v[46:49], v[162:165], v[194:197], v[46:49]
	v_mfma_f32_16x16x32_bf16 v[38:41], v[154:157], v[202:205], v[38:41]
	v_mfma_f32_16x16x32_bf16 v[30:33], v[162:165], v[202:205], v[30:33]
	v_mfma_f32_16x16x32_bf16 v[22:25], v[154:157], v[210:213], v[22:25]
	v_mfma_f32_16x16x32_bf16 v[14:17], v[162:165], v[210:213], v[14:17]
	v_mfma_f32_16x16x32_bf16 v[62:65], v[158:161], v[190:193], v[62:65]
	v_mfma_f32_16x16x32_bf16 v[58:61], v[166:169], v[190:193], v[58:61]
	v_mfma_f32_16x16x32_bf16 v[54:57], v[158:161], v[198:201], v[54:57]
	v_mfma_f32_16x16x32_bf16 v[46:49], v[166:169], v[198:201], v[46:49]
	v_mfma_f32_16x16x32_bf16 v[38:41], v[158:161], v[206:209], v[38:41]
	v_mfma_f32_16x16x32_bf16 v[30:33], v[166:169], v[206:209], v[30:33]
	v_mfma_f32_16x16x32_bf16 v[22:25], v[158:161], v[214:217], v[22:25]
	v_mfma_f32_16x16x32_bf16 v[14:17], v[166:169], v[214:217], v[14:17]
	s_setprio 0
	s_setprio 1
	v_mfma_f32_16x16x32_bf16 v[50:53], v[170:173], v[186:189], v[50:53]
	v_mfma_f32_16x16x32_bf16 v[42:45], v[178:181], v[186:189], v[42:45]
	v_mfma_f32_16x16x32_bf16 v[34:37], v[170:173], v[194:197], v[34:37]
	v_mfma_f32_16x16x32_bf16 v[26:29], v[178:181], v[194:197], v[26:29]
	v_mfma_f32_16x16x32_bf16 v[18:21], v[170:173], v[202:205], v[18:21]
	v_mfma_f32_16x16x32_bf16 v[10:13], v[178:181], v[202:205], v[10:13]
	v_mfma_f32_16x16x32_bf16 v[6:9], v[170:173], v[210:213], v[6:9]
	v_mfma_f32_16x16x32_bf16 v[2:5], v[178:181], v[210:213], v[2:5]
	v_mfma_f32_16x16x32_bf16 v[50:53], v[174:177], v[190:193], v[50:53]
	v_mfma_f32_16x16x32_bf16 v[42:45], v[182:185], v[190:193], v[42:45]
	v_mfma_f32_16x16x32_bf16 v[34:37], v[174:177], v[198:201], v[34:37]
	v_mfma_f32_16x16x32_bf16 v[26:29], v[182:185], v[198:201], v[26:29]
	v_mfma_f32_16x16x32_bf16 v[18:21], v[174:177], v[206:209], v[18:21]
	v_mfma_f32_16x16x32_bf16 v[10:13], v[182:185], v[206:209], v[10:13]
	v_mfma_f32_16x16x32_bf16 v[6:9], v[174:177], v[214:217], v[6:9]
	v_mfma_f32_16x16x32_bf16 v[2:5], v[182:185], v[214:217], v[2:5]
	s_setprio 0
	s_barrier
	s_movk_i32 s26, 0x100
	s_andn2_b64 vcc, exec, s[22:23]
	s_mov_b64 s[24:25], -1
	s_mov_b64 s[22:23], 0
	s_cbranch_vccz .LBB0_560
	s_and_b64 vcc, exec, s[14:15]
	s_cbranch_vccz .LBB0_563
	s_barrier

; #define PG8_STAGE(bufoff, gbase, voff) do { _Pragma("unroll") for (int _i = 0; _i < 2; ++_i) \
;         __builtin_amdgcn_global_load_lds((const unsigned*)((const char*)(gbase) + (voff)[_i]), (LAS unsigned*)(lds + (bufoff) + ldsw + _i * 8192), 16, 0, 0); } while (0)
; #define PG8_LDA(dst, b, h) do { _Pragma("unroll") for (int m = 0; m < 4; ++m) _Pragma("unroll") for (int k = 0; k < 2; ++k) dst[m][k] = *(const LAS bf16x8*)(lds + PG8_SA(b, h) + aoff + m * 2048 + k * 1024); } while (0)
; #define PG8_LDB(dst, b, h) do { _Pragma("unroll") for (int n = 0; n < 2; ++n) _Pragma("unroll") for (int k = 0; k < 2; ++k) dst[n][k] = *(const LAS bf16x8*)(lds + PG8_SB(b, h) + boff + n * 2048 + k * 1024); } while (0)
; #define PG8_MMA(ai, bj, At, Bt) do { __builtin_amdgcn_s_setprio(1); _Pragma("unroll") for (int m = 0; m < 4; ++m) _Pragma("unroll") for (int n = 0; n < 2; ++n) _Pragma("unroll") for (int k = 0; k < 2; ++k) \
;         acc[ai][bj][m][n] = __builtin_amdgcn_mfma_f32_16x16x32_bf16(Bt[n][k], At[m][k], acc[ai][bj][m][n], 0, 0, 0); __builtin_amdgcn_s_setprio(0); } while (0)
; #define PG8_WAIT_V(n) asm volatile("s_waitcnt vmcnt(" #n ")" ::: "memory")
; #define PG8_WAIT_L(n) asm volatile("s_waitcnt lgkmcnt(" #n ")" ::: "memory")
; #define PG8_BAR __builtin_amdgcn_s_barrier()
; #define PG8_SCHED __builtin_amdgcn_sched_barrier(0)
; template <class Epi, class Sched, bool ALIGN_EPI = false, bool SP2 = false>
; __device__ __forceinline__ void gemm_phase(LAS unsigned char* lds, const Gemm g, const Sched& S, const Epi& E) {
;     ...
;             const bool last = (t == nt - 2);
;             const char* a1 = cA + (size_t)(t + 1) * kstep;
;             const char* a2 = last ? nA : cA + (size_t)(t + 2) * kstep; const char* b2 = last ? nB : cB + (size_t)(t + 2) * kstep;
;             const char* a3 = a2 + kstep; const char* b3 = b2 + kstep;
;             if (last && has_next) S.a_ready(nxt);
;             if constexpr (SP2) {
;             PG8_LDB(B0, 0, 0); PG8_LDB(B1, 0, 1); PG8_SCHED; PG8_LDA(At, 0, 0); PG8_STAGE(PG8_SA(1, 1), a1 + hstepA, voffA);
;             PG8_WAIT_V(8); PG8_WAIT_L(0); PG8_BAR; PG8_MMA(0, 0, At, B0); PG8_MMA(0, 1, At, B1); PG8_BAR; PG8_SCHED;
;             PG8_LDA(At, 0, 1); PG8_STAGE(PG8_SB(0, 0), b2, voffB); PG8_STAGE(PG8_SB(0, 1), b2 + hstepB, voffB); PG8_STAGE(PG8_SA(0, 0), a2, voffA);
.LBB0_588:
	s_add_u32 s27, s20, s26
	s_addc_u32 s34, s21, 0
	s_add_u32 s30, s27, 0x100
	s_addc_u32 s31, s34, 0
	s_and_b64 s[28:29], s[24:25], exec
	s_cselect_b32 s29, s1, s31
	s_cselect_b32 s28, s0, s30
	s_add_u32 s26, s18, s26
	s_addc_u32 s30, s19, 0
	s_add_u32 s26, s26, 0x100
	s_addc_u32 s30, s30, 0
	s_and_b64 s[24:25], s[24:25], exec
	s_cselect_b32 s31, s17, s30
	s_cselect_b32 s30, s16, s26
	s_add_u32 s36, s27, 0x18080
	ds_read_b128 v[148:151], v142
	ds_read_b128 v[154:157], v142 offset:1024
	ds_read_b128 v[158:161], v142 offset:2048
	ds_read_b128 v[162:165], v142 offset:3072
	ds_read_b128 v[166:169], v143
	ds_read_b128 v[170:173], v143 offset:1024
	ds_read_b128 v[174:177], v143 offset:2048
	ds_read_b128 v[178:181], v143 offset:3072
	s_addc_u32 s37, s34, 0
	s_add_i32 s77, s56, s44
	s_add_i32 m0, s45, 0xc000
	s_add_i32 s78, s45, 0xe000
	s_add_i32 s72, s77, 0x2000
	s_add_u32 s34, s30, 0x18000
	s_addc_u32 s35, s31, 0
	s_add_i32 s76, s57, s44
	s_add_i32 s73, s76, 0x2000
	s_add_u32 s26, s28, 0x18000
	s_addc_u32 s27, s29, 0
	s_add_i32 s71, s59, s44
	s_add_i32 s67, s71, 0x2000
	s_add_u32 s24, s30, 0x18080
	s_addc_u32 s25, s31, 0
	s_add_i32 s70, s60, s44
	s_add_i32 s66, s70, 0x2000
	v_lshl_add_u64 v[214:215], s[36:37], 0, v[130:131]
	ds_read_b128 v[182:185], v144
	ds_read_b128 v[186:189], v144 offset:1024
	ds_read_b128 v[190:193], v144 offset:2048
	ds_read_b128 v[194:197], v144 offset:3072
	ds_read_b128 v[198:201], v144 offset:4096
	ds_read_b128 v[202:205], v144 offset:5120
	ds_read_b128 v[206:209], v144 offset:6144
	ds_read_b128 v[210:213], v144 offset:7168
	global_load_lds_dwordx4 v[214:215], off
	v_lshl_add_u64 v[214:215], s[36:37], 0, v[134:135]
	s_mov_b32 m0, s78
	s_nop 0
	global_load_lds_dwordx4 v[214:215], off
	s_waitcnt vmcnt(8)
	s_waitcnt lgkmcnt(0)
	s_setprio 1
	s_barrier
	s_waitcnt lgkmcnt(0)
	v_mfma_f32_16x16x32_bf16 v[126:129], v[148:151], v[182:185], v[126:129]
	v_mfma_f32_16x16x32_bf16 v[122:125], v[158:161], v[182:185], v[122:125]
	v_mfma_f32_16x16x32_bf16 v[118:121], v[148:151], v[190:193], v[118:121]
	v_mfma_f32_16x16x32_bf16 v[110:113], v[158:161], v[190:193], v[110:113]
	v_mfma_f32_16x16x32_bf16 v[102:105], v[148:151], v[198:201], v[102:105]
	v_mfma_f32_16x16x32_bf16 v[94:97], v[158:161], v[198:201], v[94:97]
	v_mfma_f32_16x16x32_bf16 v[86:89], v[148:151], v[206:209], v[86:89]
	v_mfma_f32_16x16x32_bf16 v[78:81], v[158:161], v[206:209], v[78:81]
	v_mfma_f32_16x16x32_bf16 v[126:129], v[154:157], v[186:189], v[126:129]
	v_mfma_f32_16x16x32_bf16 v[122:125], v[162:165], v[186:189], v[122:125]
	v_mfma_f32_16x16x32_bf16 v[118:121], v[154:157], v[194:197], v[118:121]
	v_mfma_f32_16x16x32_bf16 v[110:113], v[162:165], v[194:197], v[110:113]
	v_mfma_f32_16x16x32_bf16 v[102:105], v[154:157], v[202:205], v[102:105]
	v_mfma_f32_16x16x32_bf16 v[94:97], v[162:165], v[202:205], v[94:97]
	v_mfma_f32_16x16x32_bf16 v[86:89], v[154:157], v[210:213], v[86:89]
	v_mfma_f32_16x16x32_bf16 v[78:81], v[162:165], v[210:213], v[78:81]
	s_setprio 0
	s_setprio 1
	v_mfma_f32_16x16x32_bf16 v[114:117], v[166:169], v[182:185], v[114:117]
	v_mfma_f32_16x16x32_bf16 v[106:109], v[174:177], v[182:185], v[106:109]
	v_mfma_f32_16x16x32_bf16 v[98:101], v[166:169], v[190:193], v[98:101]
	v_mfma_f32_16x16x32_bf16 v[90:93], v[174:177], v[190:193], v[90:93]
	v_mfma_f32_16x16x32_bf16 v[82:85], v[166:169], v[198:201], v[82:85]
	v_mfma_f32_16x16x32_bf16 v[74:77], v[174:177], v[198:201], v[74:77]
	v_mfma_f32_16x16x32_bf16 v[70:73], v[166:169], v[206:209], v[70:73]
	v_mfma_f32_16x16x32_bf16 v[66:69], v[174:177], v[206:209], v[66:69]
	v_mfma_f32_16x16x32_bf16 v[114:117], v[170:173], v[186:189], v[114:117]
	v_mfma_f32_16x16x32_bf16 v[106:109], v[178:181], v[186:189], v[106:109]
	v_mfma_f32_16x16x32_bf16 v[98:101], v[170:173], v[194:197], v[98:101]
	v_mfma_f32_16x16x32_bf16 v[90:93], v[178:181], v[194:197], v[90:93]
	v_mfma_f32_16x16x32_bf16 v[82:85], v[170:173], v[202:205], v[82:85]
	v_mfma_f32_16x16x32_bf16 v[74:77], v[178:181], v[202:205], v[74:77]
	v_mfma_f32_16x16x32_bf16 v[70:73], v[170:173], v[210:213], v[70:73]
	v_mfma_f32_16x16x32_bf16 v[66:69], v[178:181], v[210:213], v[66:69]
	s_setprio 0
	s_barrier
	s_mov_b32 m0, s77
	v_lshl_add_u64 v[214:215], s[30:31], 0, v[132:133]
	ds_read_b128 v[182:185], v144 offset:16384
	ds_read_b128 v[186:189], v144 offset:17408
	ds_read_b128 v[190:193], v144 offset:18432
	ds_read_b128 v[194:197], v144 offset:19456
	ds_read_b128 v[198:201], v144 offset:20480
	ds_read_b128 v[202:205], v144 offset:21504
	ds_read_b128 v[206:209], v144 offset:22528
	ds_read_b128 v[210:213], v144 offset:23552
	global_load_lds_dwordx4 v[214:215], off
	v_lshl_add_u64 v[216:217], s[30:31], 0, v[136:137]
	s_mov_b32 m0, s72
	v_lshl_add_u64 v[218:219], s[34:35], 0, v[132:133]
	global_load_lds_dwordx4 v[216:217], off
	s_mov_b32 m0, s76
	v_lshl_add_u64 v[220:221], s[28:29], 0, v[134:135]
	global_load_lds_dwordx4 v[218:219], off
	v_lshl_add_u64 v[218:219], s[34:35], 0, v[136:137]
	s_mov_b32 m0, s73
	s_nop 0
	global_load_lds_dwordx4 v[218:219], off
	v_lshl_add_u64 v[218:219], s[28:29], 0, v[130:131]
	s_mov_b32 m0, s45
	s_nop 0
	global_load_lds_dwordx4 v[218:219], off
	s_mov_b32 m0, s46
	s_nop 0
	global_load_lds_dwordx4 v[220:221], off
	s_waitcnt vmcnt(8)
	s_waitcnt lgkmcnt(0)
	s_setprio 1
	s_barrier
; #define PG8_STAGE(bufoff, gbase, voff) do { _Pragma("unroll") for (int _i = 0; _i < 2; ++_i) \
;         __builtin_amdgcn_global_load_lds((const unsigned*)((const char*)(gbase) + (voff)[_i]), (LAS unsigned*)(lds + (bufoff) + ldsw + _i * 8192), 16, 0, 0); } while (0)
; #define PG8_LDA(dst, b, h) do { _Pragma("unroll") for (int m = 0; m < 4; ++m) _Pragma("unroll") for (int k = 0; k < 2; ++k) dst[m][k] = *(const LAS bf16x8*)(lds + PG8_SA(b, h) + aoff + m * 2048 + k * 1024); } while (0)
; #define PG8_LDB(dst, b, h) do { _Pragma("unroll") for (int n = 0; n < 2; ++n) _Pragma("unroll") for (int k = 0; k < 2; ++k) dst[n][k] = *(const LAS bf16x8*)(lds + PG8_SB(b, h) + boff + n * 2048 + k * 1024); } while (0)
; #define PG8_MMA(ai, bj, At, Bt) do { __builtin_amdgcn_s_setprio(1); _Pragma("unroll") for (int m = 0; m < 4; ++m) _Pragma("unroll") for (int n = 0; n < 2; ++n) _Pragma("unroll") for (int k = 0; k < 2; ++k) \
;         acc[ai][bj][m][n] = __builtin_amdgcn_mfma_f32_16x16x32_bf16(Bt[n][k], At[m][k], acc[ai][bj][m][n], 0, 0, 0); __builtin_amdgcn_s_setprio(0); } while (0)
; #define PG8_WAIT_V(n) asm volatile("s_waitcnt vmcnt(" #n ")" ::: "memory")
; #define PG8_WAIT_L(n) asm volatile("s_waitcnt lgkmcnt(" #n ")" ::: "memory")
; #define PG8_BAR __builtin_amdgcn_s_barrier()
; #define PG8_SCHED __builtin_amdgcn_sched_barrier(0)
; template <class Epi, class Sched, bool ALIGN_EPI = false, bool SP2 = false>
; __device__ __forceinline__ void gemm_phase(LAS unsigned char* lds, const Gemm g, const Sched& S, const Epi& E) {
;     ...
;             PG8_WAIT_V(8); PG8_WAIT_L(0); PG8_BAR; PG8_MMA(1, 0, At, B0); PG8_MMA(1, 1, At, B1); PG8_BAR; PG8_SCHED;
;             PG8_LDB(B0, 1, 0); PG8_LDB(B1, 1, 1); PG8_SCHED; PG8_LDA(At, 1, 0); PG8_STAGE(PG8_SA(0, 1), a2 + hstepA, voffA);
;             PG8_WAIT_V(8); PG8_WAIT_L(0); PG8_BAR; PG8_MMA(0, 0, At, B0); PG8_MMA(0, 1, At, B1); PG8_BAR; PG8_SCHED;
	s_waitcnt lgkmcnt(0)
	v_mfma_f32_16x16x32_bf16 v[62:65], v[148:151], v[182:185], v[62:65]
	v_mfma_f32_16x16x32_bf16 v[58:61], v[158:161], v[182:185], v[58:61]
	v_mfma_f32_16x16x32_bf16 v[54:57], v[148:151], v[190:193], v[54:57]
	v_mfma_f32_16x16x32_bf16 v[46:49], v[158:161], v[190:193], v[46:49]
	v_mfma_f32_16x16x32_bf16 v[38:41], v[148:151], v[198:201], v[38:41]
	v_mfma_f32_16x16x32_bf16 v[30:33], v[158:161], v[198:201], v[30:33]
	v_mfma_f32_16x16x32_bf16 v[22:25], v[148:151], v[206:209], v[22:25]
	v_mfma_f32_16x16x32_bf16 v[14:17], v[158:161], v[206:209], v[14:17]
	v_mfma_f32_16x16x32_bf16 v[62:65], v[154:157], v[186:189], v[62:65]
	v_mfma_f32_16x16x32_bf16 v[58:61], v[162:165], v[186:189], v[58:61]
	v_mfma_f32_16x16x32_bf16 v[54:57], v[154:157], v[194:197], v[54:57]
	v_mfma_f32_16x16x32_bf16 v[46:49], v[162:165], v[194:197], v[46:49]
	v_mfma_f32_16x16x32_bf16 v[38:41], v[154:157], v[202:205], v[38:41]
	v_mfma_f32_16x16x32_bf16 v[30:33], v[162:165], v[202:205], v[30:33]
	v_mfma_f32_16x16x32_bf16 v[22:25], v[154:157], v[210:213], v[22:25]
	v_mfma_f32_16x16x32_bf16 v[14:17], v[162:165], v[210:213], v[14:17]
	s_setprio 0
	s_setprio 1
	v_mfma_f32_16x16x32_bf16 v[50:53], v[166:169], v[182:185], v[50:53]
	v_mfma_f32_16x16x32_bf16 v[42:45], v[174:177], v[182:185], v[42:45]
	v_mfma_f32_16x16x32_bf16 v[34:37], v[166:169], v[190:193], v[34:37]
	v_mfma_f32_16x16x32_bf16 v[26:29], v[174:177], v[190:193], v[26:29]
	v_mfma_f32_16x16x32_bf16 v[18:21], v[166:169], v[198:201], v[18:21]
	v_mfma_f32_16x16x32_bf16 v[10:13], v[174:177], v[198:201], v[10:13]
	v_mfma_f32_16x16x32_bf16 v[6:9], v[166:169], v[206:209], v[6:9]
	v_mfma_f32_16x16x32_bf16 v[2:5], v[174:177], v[206:209], v[2:5]
	v_mfma_f32_16x16x32_bf16 v[50:53], v[170:173], v[186:189], v[50:53]
	v_mfma_f32_16x16x32_bf16 v[42:45], v[178:181], v[186:189], v[42:45]
	v_mfma_f32_16x16x32_bf16 v[34:37], v[170:173], v[194:197], v[34:37]
	v_mfma_f32_16x16x32_bf16 v[26:29], v[178:181], v[194:197], v[26:29]
	v_mfma_f32_16x16x32_bf16 v[18:21], v[170:173], v[202:205], v[18:21]
	v_mfma_f32_16x16x32_bf16 v[10:13], v[178:181], v[202:205], v[10:13]
	v_mfma_f32_16x16x32_bf16 v[6:9], v[170:173], v[210:213], v[6:9]
	v_mfma_f32_16x16x32_bf16 v[2:5], v[178:181], v[210:213], v[2:5]
	s_setprio 0
	s_barrier
	ds_read_b128 v[148:151], v146
	ds_read_b128 v[154:157], v146 offset:1024
	ds_read_b128 v[158:161], v146 offset:2048
	ds_read_b128 v[162:165], v146 offset:3072
	ds_read_b128 v[166:169], v147
	ds_read_b128 v[170:173], v147 offset:1024
	ds_read_b128 v[174:177], v147 offset:2048
	ds_read_b128 v[178:181], v147 offset:3072
	s_mov_b32 m0, s47
	v_lshl_add_u64 v[222:223], s[26:27], 0, v[130:131]
	ds_read_b128 v[182:185], v144 offset:32768
	ds_read_b128 v[186:189], v144 offset:33792
	ds_read_b128 v[190:193], v144 offset:34816
	ds_read_b128 v[194:197], v144 offset:35840
	ds_read_b128 v[198:201], v144 offset:36864
	ds_read_b128 v[202:205], v144 offset:37888
	ds_read_b128 v[206:209], v144 offset:38912
	ds_read_b128 v[210:213], v144 offset:39936
	global_load_lds_dwordx4 v[222:223], off
	v_lshl_add_u64 v[222:223], s[26:27], 0, v[134:135]
	s_mov_b32 m0, s50
	s_nop 0
	global_load_lds_dwordx4 v[222:223], off
	s_waitcnt vmcnt(8)
	s_waitcnt lgkmcnt(0)
	s_setprio 1
	s_barrier
	s_waitcnt lgkmcnt(0)
	v_mfma_f32_16x16x32_bf16 v[126:129], v[148:151], v[182:185], v[126:129]
	v_mfma_f32_16x16x32_bf16 v[122:125], v[158:161], v[182:185], v[122:125]
	v_mfma_f32_16x16x32_bf16 v[118:121], v[148:151], v[190:193], v[118:121]
	v_mfma_f32_16x16x32_bf16 v[110:113], v[158:161], v[190:193], v[110:113]
	v_mfma_f32_16x16x32_bf16 v[102:105], v[148:151], v[198:201], v[102:105]
	v_mfma_f32_16x16x32_bf16 v[94:97], v[158:161], v[198:201], v[94:97]
	v_mfma_f32_16x16x32_bf16 v[86:89], v[148:151], v[206:209], v[86:89]
	v_mfma_f32_16x16x32_bf16 v[78:81], v[158:161], v[206:209], v[78:81]
	v_mfma_f32_16x16x32_bf16 v[126:129], v[154:157], v[186:189], v[126:129]
	v_mfma_f32_16x16x32_bf16 v[122:125], v[162:165], v[186:189], v[122:125]
	v_mfma_f32_16x16x32_bf16 v[118:121], v[154:157], v[194:197], v[118:121]
	v_mfma_f32_16x16x32_bf16 v[110:113], v[162:165], v[194:197], v[110:113]
	v_mfma_f32_16x16x32_bf16 v[102:105], v[154:157], v[202:205], v[102:105]
	v_mfma_f32_16x16x32_bf16 v[94:97], v[162:165], v[202:205], v[94:97]
	v_mfma_f32_16x16x32_bf16 v[86:89], v[154:157], v[210:213], v[86:89]
	v_mfma_f32_16x16x32_bf16 v[78:81], v[162:165], v[210:213], v[78:81]
	s_setprio 0
	s_setprio 1
	v_mfma_f32_16x16x32_bf16 v[114:117], v[166:169], v[182:185], v[114:117]
	v_mfma_f32_16x16x32_bf16 v[106:109], v[174:177], v[182:185], v[106:109]
	v_mfma_f32_16x16x32_bf16 v[98:101], v[166:169], v[190:193], v[98:101]
	v_mfma_f32_16x16x32_bf16 v[90:93], v[174:177], v[190:193], v[90:93]
	v_mfma_f32_16x16x32_bf16 v[82:85], v[166:169], v[198:201], v[82:85]
	v_mfma_f32_16x16x32_bf16 v[74:77], v[174:177], v[198:201], v[74:77]
	v_mfma_f32_16x16x32_bf16 v[70:73], v[166:169], v[206:209], v[70:73]
	v_mfma_f32_16x16x32_bf16 v[66:69], v[174:177], v[206:209], v[66:69]
	v_mfma_f32_16x16x32_bf16 v[114:117], v[170:173], v[186:189], v[114:117]
	v_mfma_f32_16x16x32_bf16 v[106:109], v[178:181], v[186:189], v[106:109]
	v_mfma_f32_16x16x32_bf16 v[98:101], v[170:173], v[194:197], v[98:101]
	v_mfma_f32_16x16x32_bf16 v[90:93], v[178:181], v[194:197], v[90:93]
	v_mfma_f32_16x16x32_bf16 v[82:85], v[170:173], v[202:205], v[82:85]
	v_mfma_f32_16x16x32_bf16 v[74:77], v[178:181], v[202:205], v[74:77]
	v_mfma_f32_16x16x32_bf16 v[70:73], v[170:173], v[210:213], v[70:73]
	v_mfma_f32_16x16x32_bf16 v[66:69], v[178:181], v[210:213], v[66:69]
	s_setprio 0
	s_barrier
; #define PG8_STAGE(bufoff, gbase, voff) do { _Pragma("unroll") for (int _i = 0; _i < 2; ++_i) \
;         __builtin_amdgcn_global_load_lds((const unsigned*)((const char*)(gbase) + (voff)[_i]), (LAS unsigned*)(lds + (bufoff) + ldsw + _i * 8192), 16, 0, 0); } while (0)
; #define PG8_LDA(dst, b, h) do { _Pragma("unroll") for (int m = 0; m < 4; ++m) _Pragma("unroll") for (int k = 0; k < 2; ++k) dst[m][k] = *(const LAS bf16x8*)(lds + PG8_SA(b, h) + aoff + m * 2048 + k * 1024); } while (0)
; #define PG8_MMA(ai, bj, At, Bt) do { __builtin_amdgcn_s_setprio(1); _Pragma("unroll") for (int m = 0; m < 4; ++m) _Pragma("unroll") for (int n = 0; n < 2; ++n) _Pragma("unroll") for (int k = 0; k < 2; ++k) \
;         acc[ai][bj][m][n] = __builtin_amdgcn_mfma_f32_16x16x32_bf16(Bt[n][k], At[m][k], acc[ai][bj][m][n], 0, 0, 0); __builtin_amdgcn_s_setprio(0); } while (0)
; #define PG8_WAIT_V(n) asm volatile("s_waitcnt vmcnt(" #n ")" ::: "memory")
; #define PG8_WAIT_L(n) asm volatile("s_waitcnt lgkmcnt(" #n ")" ::: "memory")
; #define PG8_BAR __builtin_amdgcn_s_barrier()
; #define PG8_SCHED __builtin_amdgcn_sched_barrier(0)
; template <class Epi, class Sched, bool ALIGN_EPI = false, bool SP2 = false>
; __device__ __forceinline__ void gemm_phase(LAS unsigned char* lds, const Gemm g, const Sched& S, const Epi& E) {
;     ...
;             PG8_LDA(At, 1, 1); PG8_STAGE(PG8_SB(1, 0), b3, voffB); PG8_STAGE(PG8_SB(1, 1), b3 + hstepB, voffB); PG8_STAGE(PG8_SA(1, 0), a3, voffA);
;             PG8_WAIT_V(8); PG8_WAIT_L(0); PG8_BAR; PG8_MMA(1, 0, At, B0); PG8_MMA(1, 1, At, B1); PG8_BAR; PG8_SCHED;
	s_mov_b32 m0, s71
	v_lshl_add_u64 v[214:215], v[214:215], 0, s[12:13]
	ds_read_b128 v[182:185], v144 offset:49152
	ds_read_b128 v[186:189], v144 offset:50176
	ds_read_b128 v[190:193], v144 offset:51200
	ds_read_b128 v[194:197], v144 offset:52224
	ds_read_b128 v[198:201], v144 offset:53248
	ds_read_b128 v[202:205], v144 offset:54272
	ds_read_b128 v[206:209], v144 offset:55296
	ds_read_b128 v[210:213], v144 offset:56320
	global_load_lds_dwordx4 v[214:215], off
	v_lshl_add_u64 v[214:215], v[216:217], 0, s[12:13]
	s_mov_b32 m0, s67
	s_nop 0
	global_load_lds_dwordx4 v[214:215], off
	v_lshl_add_u64 v[214:215], s[24:25], 0, v[132:133]
	s_mov_b32 m0, s70
	s_nop 0
	global_load_lds_dwordx4 v[214:215], off
	v_lshl_add_u64 v[214:215], s[24:25], 0, v[136:137]
	s_mov_b32 m0, s66
	s_nop 0
	global_load_lds_dwordx4 v[214:215], off
	v_lshl_add_u64 v[214:215], v[218:219], 0, s[12:13]
	s_mov_b32 m0, s51
	s_nop 0
	global_load_lds_dwordx4 v[214:215], off
	v_lshl_add_u64 v[214:215], v[220:221], 0, s[12:13]
	s_mov_b32 m0, s52
	s_nop 0
	global_load_lds_dwordx4 v[214:215], off
	s_waitcnt vmcnt(8)
	s_waitcnt lgkmcnt(0)
	s_setprio 1
	s_barrier
	s_waitcnt lgkmcnt(0)
	v_mfma_f32_16x16x32_bf16 v[62:65], v[148:151], v[182:185], v[62:65]
	v_mfma_f32_16x16x32_bf16 v[58:61], v[158:161], v[182:185], v[58:61]
	v_mfma_f32_16x16x32_bf16 v[54:57], v[148:151], v[190:193], v[54:57]
	v_mfma_f32_16x16x32_bf16 v[46:49], v[158:161], v[190:193], v[46:49]
	v_mfma_f32_16x16x32_bf16 v[38:41], v[148:151], v[198:201], v[38:41]
	v_mfma_f32_16x16x32_bf16 v[30:33], v[158:161], v[198:201], v[30:33]
	v_mfma_f32_16x16x32_bf16 v[22:25], v[148:151], v[206:209], v[22:25]
	v_mfma_f32_16x16x32_bf16 v[14:17], v[158:161], v[206:209], v[14:17]
	v_mfma_f32_16x16x32_bf16 v[62:65], v[154:157], v[186:189], v[62:65]
	v_mfma_f32_16x16x32_bf16 v[58:61], v[162:165], v[186:189], v[58:61]
	v_mfma_f32_16x16x32_bf16 v[54:57], v[154:157], v[194:197], v[54:57]
	v_mfma_f32_16x16x32_bf16 v[46:49], v[162:165], v[194:197], v[46:49]
	v_mfma_f32_16x16x32_bf16 v[38:41], v[154:157], v[202:205], v[38:41]
	v_mfma_f32_16x16x32_bf16 v[30:33], v[162:165], v[202:205], v[30:33]
	v_mfma_f32_16x16x32_bf16 v[22:25], v[154:157], v[210:213], v[22:25]
	v_mfma_f32_16x16x32_bf16 v[14:17], v[162:165], v[210:213], v[14:17]
	s_setprio 0
	s_setprio 1
	v_mfma_f32_16x16x32_bf16 v[50:53], v[166:169], v[182:185], v[50:53]
	v_mfma_f32_16x16x32_bf16 v[42:45], v[174:177], v[182:185], v[42:45]
	v_mfma_f32_16x16x32_bf16 v[34:37], v[166:169], v[190:193], v[34:37]
	v_mfma_f32_16x16x32_bf16 v[26:29], v[174:177], v[190:193], v[26:29]
	v_mfma_f32_16x16x32_bf16 v[18:21], v[166:169], v[198:201], v[18:21]
	v_mfma_f32_16x16x32_bf16 v[10:13], v[174:177], v[198:201], v[10:13]
	v_mfma_f32_16x16x32_bf16 v[6:9], v[166:169], v[206:209], v[6:9]
	v_mfma_f32_16x16x32_bf16 v[2:5], v[174:177], v[206:209], v[2:5]
	v_mfma_f32_16x16x32_bf16 v[50:53], v[170:173], v[186:189], v[50:53]
	v_mfma_f32_16x16x32_bf16 v[42:45], v[178:181], v[186:189], v[42:45]
	v_mfma_f32_16x16x32_bf16 v[34:37], v[170:173], v[194:197], v[34:37]
	v_mfma_f32_16x16x32_bf16 v[26:29], v[178:181], v[194:197], v[26:29]
	v_mfma_f32_16x16x32_bf16 v[18:21], v[170:173], v[202:205], v[18:21]
	v_mfma_f32_16x16x32_bf16 v[10:13], v[178:181], v[202:205], v[10:13]
	v_mfma_f32_16x16x32_bf16 v[6:9], v[170:173], v[210:213], v[6:9]
	v_mfma_f32_16x16x32_bf16 v[2:5], v[178:181], v[210:213], v[2:5]
	s_setprio 0
	s_barrier
	s_movk_i32 s26, 0x100
	s_andn2_b64 vcc, exec, s[22:23]
	s_mov_b64 s[24:25], -1
	s_mov_b64 s[22:23], 0
	s_cbranch_vccz .LBB0_588
	s_and_b64 vcc, exec, s[14:15]
	s_cbranch_vccz .LBB0_591
	s_barrier

; #define PG8_STAGE(bufoff, gbase, voff) do { _Pragma("unroll") for (int _i = 0; _i < 2; ++_i) \
;         __builtin_amdgcn_global_load_lds((const unsigned*)((const char*)(gbase) + (voff)[_i]), (LAS unsigned*)(lds + (bufoff) + ldsw + _i * 8192), 16, 0, 0); } while (0)
; #define PG8_LDA(dst, b, h) do { _Pragma("unroll") for (int m = 0; m < 4; ++m) _Pragma("unroll") for (int k = 0; k < 2; ++k) dst[m][k] = *(const LAS bf16x8*)(lds + PG8_SA(b, h) + aoff + m * 2048 + k * 1024); } while (0)
; #define PG8_LDB(dst, b, h) do { _Pragma("unroll") for (int n = 0; n < 2; ++n) _Pragma("unroll") for (int k = 0; k < 2; ++k) dst[n][k] = *(const LAS bf16x8*)(lds + PG8_SB(b, h) + boff + n * 2048 + k * 1024); } while (0)
; #define PG8_MMA(ai, bj, At, Bt) do { __builtin_amdgcn_s_setprio(1); _Pragma("unroll") for (int m = 0; m < 4; ++m) _Pragma("unroll") for (int n = 0; n < 2; ++n) _Pragma("unroll") for (int k = 0; k < 2; ++k) \
;         acc[ai][bj][m][n] = __builtin_amdgcn_mfma_f32_16x16x32_bf16(Bt[n][k], At[m][k], acc[ai][bj][m][n], 0, 0, 0); __builtin_amdgcn_s_setprio(0); } while (0)
; #define PG8_WAIT_V(n) asm volatile("s_waitcnt vmcnt(" #n ")" ::: "memory")
; #define PG8_WAIT_L(n) asm volatile("s_waitcnt lgkmcnt(" #n ")" ::: "memory")
; #define PG8_BAR __builtin_amdgcn_s_barrier()
; template <class Epi, class Sched, bool ALIGN_EPI = false, bool SP2 = false>
; __device__ __forceinline__ void gemm_phase(LAS unsigned char* lds, const Gemm g, const Sched& S, const Epi& E) {
;     ...
;             const bool last = (t == nt - 2);
;             const char* a1 = cA + (size_t)(t + 1) * kstep;
;             const char* a2 = last ? nA : cA + (size_t)(t + 2) * kstep; const char* b2 = last ? nB : cB + (size_t)(t + 2) * kstep;
;             const char* a3 = a2 + kstep; const char* b3 = b2 + kstep;
;             if (last && has_next) S.a_ready(nxt);
;             if constexpr (SP2) {
;             PG8_LDB(B0, 0, 0); PG8_LDB(B1, 0, 1); PG8_SCHED; PG8_LDA(At, 0, 0); PG8_STAGE(PG8_SA(1, 1), a1 + hstepA, voffA);
;             PG8_WAIT_V(8); PG8_WAIT_L(0); PG8_BAR; PG8_MMA(0, 0, At, B0); PG8_MMA(0, 1, At, B1); PG8_BAR; PG8_SCHED;
;             PG8_LDA(At, 0, 1); PG8_STAGE(PG8_SB(0, 0), b2, voffB); PG8_STAGE(PG8_SB(0, 1), b2 + hstepB, voffB); PG8_STAGE(PG8_SA(0, 0), a2, voffA);
;             PG8_WAIT_V(8); PG8_WAIT_L(0); PG8_BAR; PG8_MMA(1, 0, At, B0); PG8_MMA(1, 1, At, B1); PG8_BAR; PG8_SCHED;
.LBB0_968:
	ds_read_b128 v[120:123], v221
	ds_read_b128 v[124:127], v221 offset:1024
	ds_read_b128 v[136:139], v221 offset:2048
	ds_read_b128 v[140:143], v221 offset:3072
	ds_read_b128 v[144:147], v222
	ds_read_b128 v[148:151], v222 offset:1024
	ds_read_b128 v[170:173], v222 offset:2048
	ds_read_b128 v[174:177], v222 offset:3072
	s_add_u32 s28, s26, 0xfff80080
	s_addc_u32 s29, s27, -1
	s_cmp_eq_u32 s50, 28
	s_cselect_b32 s31, s17, s29
	s_cselect_b32 s30, s23, s28
	s_cselect_b32 s29, s15, s49
	s_cselect_b32 s28, s25, s33
	v_lshl_add_u64 v[210:211], s[26:27], 0, v[162:163]
	s_add_i32 m0, s35, 0xc000
	ds_read_b128 v[178:181], v223
	ds_read_b128 v[182:185], v223 offset:1024
	ds_read_b128 v[186:189], v223 offset:2048
	ds_read_b128 v[190:193], v223 offset:3072
	ds_read_b128 v[194:197], v223 offset:4096
	ds_read_b128 v[198:201], v223 offset:5120
	ds_read_b128 v[202:205], v223 offset:6144
	ds_read_b128 v[206:209], v223 offset:7168
	global_load_lds_dwordx4 v[210:211], off
	v_lshl_add_u64 v[210:211], s[26:27], 0, v[164:165]
	s_add_i32 m0, s35, 0xe000
	s_nop 0
	global_load_lds_dwordx4 v[210:211], off
	s_waitcnt vmcnt(8)
	s_waitcnt lgkmcnt(0)
	s_setprio 1
	s_barrier
	s_waitcnt lgkmcnt(0)
	v_mfma_f32_16x16x32_bf16 v[132:135], v[120:123], v[178:181], v[132:135]
	v_mfma_f32_16x16x32_bf16 v[128:131], v[136:139], v[178:181], v[128:131]
	v_mfma_f32_16x16x32_bf16 v[100:103], v[120:123], v[186:189], v[100:103]
	v_mfma_f32_16x16x32_bf16 v[96:99], v[136:139], v[186:189], v[96:99]
	v_mfma_f32_16x16x32_bf16 v[116:119], v[120:123], v[194:197], v[116:119]
	v_mfma_f32_16x16x32_bf16 v[112:115], v[136:139], v[194:197], v[112:115]
	v_mfma_f32_16x16x32_bf16 v[108:111], v[120:123], v[202:205], v[108:111]
	v_mfma_f32_16x16x32_bf16 v[104:107], v[136:139], v[202:205], v[104:107]
	v_mfma_f32_16x16x32_bf16 v[132:135], v[124:127], v[182:185], v[132:135]
	v_mfma_f32_16x16x32_bf16 v[128:131], v[140:143], v[182:185], v[128:131]
	v_mfma_f32_16x16x32_bf16 v[100:103], v[124:127], v[190:193], v[100:103]
	v_mfma_f32_16x16x32_bf16 v[96:99], v[140:143], v[190:193], v[96:99]
	v_mfma_f32_16x16x32_bf16 v[116:119], v[124:127], v[198:201], v[116:119]
	v_mfma_f32_16x16x32_bf16 v[112:115], v[140:143], v[198:201], v[112:115]
	v_mfma_f32_16x16x32_bf16 v[108:111], v[124:127], v[206:209], v[108:111]
	v_mfma_f32_16x16x32_bf16 v[104:107], v[140:143], v[206:209], v[104:107]
	s_setprio 0
	s_setprio 1
	v_mfma_f32_16x16x32_bf16 v[60:63], v[144:147], v[178:181], v[60:63]
	v_mfma_f32_16x16x32_bf16 v[56:59], v[170:173], v[178:181], v[56:59]
	v_mfma_f32_16x16x32_bf16 v[52:55], v[144:147], v[186:189], v[52:55]
	v_mfma_f32_16x16x32_bf16 v[48:51], v[170:173], v[186:189], v[48:51]
	v_mfma_f32_16x16x32_bf16 v[44:47], v[144:147], v[194:197], v[44:47]
	v_mfma_f32_16x16x32_bf16 v[40:43], v[170:173], v[194:197], v[40:43]
	v_mfma_f32_16x16x32_bf16 v[36:39], v[144:147], v[202:205], v[36:39]
	v_mfma_f32_16x16x32_bf16 v[32:35], v[170:173], v[202:205], v[32:35]
	v_mfma_f32_16x16x32_bf16 v[60:63], v[148:151], v[182:185], v[60:63]
	v_mfma_f32_16x16x32_bf16 v[56:59], v[174:177], v[182:185], v[56:59]
	v_mfma_f32_16x16x32_bf16 v[52:55], v[148:151], v[190:193], v[52:55]
	v_mfma_f32_16x16x32_bf16 v[48:51], v[174:177], v[190:193], v[48:51]
	v_mfma_f32_16x16x32_bf16 v[44:47], v[148:151], v[198:201], v[44:47]
	v_mfma_f32_16x16x32_bf16 v[40:43], v[174:177], v[198:201], v[40:43]
	v_mfma_f32_16x16x32_bf16 v[36:39], v[148:151], v[206:209], v[36:39]
	v_mfma_f32_16x16x32_bf16 v[32:35], v[174:177], v[206:209], v[32:35]
	s_setprio 0
	s_barrier
	s_add_i32 s51, s45, s34
	v_lshl_add_u64 v[210:211], s[28:29], 0, v[156:157]
	s_mov_b32 m0, s51
	ds_read_b128 v[178:181], v223 offset:16384
	ds_read_b128 v[182:185], v223 offset:17408
	ds_read_b128 v[186:189], v223 offset:18432
	ds_read_b128 v[190:193], v223 offset:19456
	ds_read_b128 v[194:197], v223 offset:20480
	ds_read_b128 v[198:201], v223 offset:21504
	ds_read_b128 v[202:205], v223 offset:22528
	ds_read_b128 v[206:209], v223 offset:23552
	global_load_lds_dwordx4 v[210:211], off
	s_add_i32 m0, s51, 0x2000
	s_add_u32 s52, s28, 0x80000
	v_lshl_add_u64 v[212:213], s[28:29], 0, v[160:161]
	s_addc_u32 s53, s29, 0
	s_add_i32 s51, s46, s34
	global_load_lds_dwordx4 v[212:213], off
	v_lshl_add_u64 v[214:215], s[52:53], 0, v[156:157]
	s_mov_b32 m0, s51
	v_lshl_add_u64 v[216:217], s[30:31], 0, v[158:159]
	global_load_lds_dwordx4 v[214:215], off
	v_lshl_add_u64 v[214:215], s[52:53], 0, v[160:161]
	s_add_i32 m0, s51, 0x2000
	s_nop 0
	global_load_lds_dwordx4 v[214:215], off
	v_lshl_add_u64 v[214:215], s[30:31], 0, v[154:155]
	s_mov_b32 m0, s35
	s_nop 0
	global_load_lds_dwordx4 v[214:215], off
	s_mov_b32 m0, s36
	s_nop 0
	global_load_lds_dwordx4 v[216:217], off
	s_waitcnt vmcnt(8)
	s_waitcnt lgkmcnt(0)
	s_setprio 1
	s_barrier
; #define PG8_STAGE(bufoff, gbase, voff) do { _Pragma("unroll") for (int _i = 0; _i < 2; ++_i) \
;         __builtin_amdgcn_global_load_lds((const unsigned*)((const char*)(gbase) + (voff)[_i]), (LAS unsigned*)(lds + (bufoff) + ldsw + _i * 8192), 16, 0, 0); } while (0)
; #define PG8_LDA(dst, b, h) do { _Pragma("unroll") for (int m = 0; m < 4; ++m) _Pragma("unroll") for (int k = 0; k < 2; ++k) dst[m][k] = *(const LAS bf16x8*)(lds + PG8_SA(b, h) + aoff + m * 2048 + k * 1024); } while (0)
; #define PG8_LDB(dst, b, h) do { _Pragma("unroll") for (int n = 0; n < 2; ++n) _Pragma("unroll") for (int k = 0; k < 2; ++k) dst[n][k] = *(const LAS bf16x8*)(lds + PG8_SB(b, h) + boff + n * 2048 + k * 1024); } while (0)
; #define PG8_MMA(ai, bj, At, Bt) do { __builtin_amdgcn_s_setprio(1); _Pragma("unroll") for (int m = 0; m < 4; ++m) _Pragma("unroll") for (int n = 0; n < 2; ++n) _Pragma("unroll") for (int k = 0; k < 2; ++k) \
;         acc[ai][bj][m][n] = __builtin_amdgcn_mfma_f32_16x16x32_bf16(Bt[n][k], At[m][k], acc[ai][bj][m][n], 0, 0, 0); __builtin_amdgcn_s_setprio(0); } while (0)
; #define PG8_WAIT_V(n) asm volatile("s_waitcnt vmcnt(" #n ")" ::: "memory")
; #define PG8_WAIT_L(n) asm volatile("s_waitcnt lgkmcnt(" #n ")" ::: "memory")
; #define PG8_BAR __builtin_amdgcn_s_barrier()
; #define PG8_SCHED __builtin_amdgcn_sched_barrier(0)
; template <class Epi, class Sched, bool ALIGN_EPI = false, bool SP2 = false>
; __device__ __forceinline__ void gemm_phase(LAS unsigned char* lds, const Gemm g, const Sched& S, const Epi& E) {
;     ...
;             PG8_WAIT_V(8); PG8_WAIT_L(0); PG8_BAR; PG8_MMA(1, 0, At, B0); PG8_MMA(1, 1, At, B1); PG8_BAR; PG8_SCHED;
;             PG8_LDB(B0, 1, 0); PG8_LDB(B1, 1, 1); PG8_SCHED; PG8_LDA(At, 1, 0); PG8_STAGE(PG8_SA(0, 1), a2 + hstepA, voffA);
;             PG8_WAIT_V(8); PG8_WAIT_L(0); PG8_BAR; PG8_MMA(0, 0, At, B0); PG8_MMA(0, 1, At, B1); PG8_BAR; PG8_SCHED;
	s_waitcnt lgkmcnt(0)
	v_mfma_f32_16x16x32_bf16 v[92:95], v[120:123], v[178:181], v[92:95]
	v_mfma_f32_16x16x32_bf16 v[88:91], v[136:139], v[178:181], v[88:91]
	v_mfma_f32_16x16x32_bf16 v[84:87], v[120:123], v[186:189], v[84:87]
	v_mfma_f32_16x16x32_bf16 v[80:83], v[136:139], v[186:189], v[80:83]
	v_mfma_f32_16x16x32_bf16 v[76:79], v[120:123], v[194:197], v[76:79]
	v_mfma_f32_16x16x32_bf16 v[72:75], v[136:139], v[194:197], v[72:75]
	v_mfma_f32_16x16x32_bf16 v[68:71], v[120:123], v[202:205], v[68:71]
	v_mfma_f32_16x16x32_bf16 v[64:67], v[136:139], v[202:205], v[64:67]
	v_mfma_f32_16x16x32_bf16 v[92:95], v[124:127], v[182:185], v[92:95]
	v_mfma_f32_16x16x32_bf16 v[88:91], v[140:143], v[182:185], v[88:91]
	v_mfma_f32_16x16x32_bf16 v[84:87], v[124:127], v[190:193], v[84:87]
	v_mfma_f32_16x16x32_bf16 v[80:83], v[140:143], v[190:193], v[80:83]
	v_mfma_f32_16x16x32_bf16 v[76:79], v[124:127], v[198:201], v[76:79]
	v_mfma_f32_16x16x32_bf16 v[72:75], v[140:143], v[198:201], v[72:75]
	v_mfma_f32_16x16x32_bf16 v[68:71], v[124:127], v[206:209], v[68:71]
	v_mfma_f32_16x16x32_bf16 v[64:67], v[140:143], v[206:209], v[64:67]
	s_setprio 0
	s_setprio 1
	v_mfma_f32_16x16x32_bf16 v[28:31], v[144:147], v[178:181], v[28:31]
	v_mfma_f32_16x16x32_bf16 v[24:27], v[170:173], v[178:181], v[24:27]
	v_mfma_f32_16x16x32_bf16 v[20:23], v[144:147], v[186:189], v[20:23]
	v_mfma_f32_16x16x32_bf16 v[16:19], v[170:173], v[186:189], v[16:19]
	v_mfma_f32_16x16x32_bf16 v[12:15], v[144:147], v[194:197], v[12:15]
	v_mfma_f32_16x16x32_bf16 v[8:11], v[170:173], v[194:197], v[8:11]
	v_mfma_f32_16x16x32_bf16 v[4:7], v[144:147], v[202:205], v[4:7]
	v_mfma_f32_16x16x32_bf16 v[0:3], v[170:173], v[202:205], v[0:3]
	v_mfma_f32_16x16x32_bf16 v[28:31], v[148:151], v[182:185], v[28:31]
	v_mfma_f32_16x16x32_bf16 v[24:27], v[174:177], v[182:185], v[24:27]
	v_mfma_f32_16x16x32_bf16 v[20:23], v[148:151], v[190:193], v[20:23]
	v_mfma_f32_16x16x32_bf16 v[16:19], v[174:177], v[190:193], v[16:19]
	v_mfma_f32_16x16x32_bf16 v[12:15], v[148:151], v[198:201], v[12:15]
	v_mfma_f32_16x16x32_bf16 v[8:11], v[174:177], v[198:201], v[8:11]
	v_mfma_f32_16x16x32_bf16 v[4:7], v[148:151], v[206:209], v[4:7]
	v_mfma_f32_16x16x32_bf16 v[0:3], v[174:177], v[206:209], v[0:3]
	s_setprio 0
	s_barrier
	ds_read_b128 v[120:123], v225
	ds_read_b128 v[124:127], v225 offset:1024
	ds_read_b128 v[136:139], v225 offset:2048
	ds_read_b128 v[140:143], v225 offset:3072
	ds_read_b128 v[144:147], v226
	ds_read_b128 v[148:151], v226 offset:1024
	ds_read_b128 v[170:173], v226 offset:2048
	ds_read_b128 v[174:177], v226 offset:3072
	s_add_u32 s30, s30, 0x80000
	s_addc_u32 s31, s31, 0
	s_mov_b32 m0, s37
	v_lshl_add_u64 v[218:219], s[30:31], 0, v[154:155]
	ds_read_b128 v[178:181], v223 offset:32768
	ds_read_b128 v[182:185], v223 offset:33792
	ds_read_b128 v[186:189], v223 offset:34816
	ds_read_b128 v[190:193], v223 offset:35840
	ds_read_b128 v[194:197], v223 offset:36864
	ds_read_b128 v[198:201], v223 offset:37888
	ds_read_b128 v[202:205], v223 offset:38912
	ds_read_b128 v[206:209], v223 offset:39936
	global_load_lds_dwordx4 v[218:219], off
	v_lshl_add_u64 v[218:219], s[30:31], 0, v[158:159]
	s_mov_b32 m0, s38
	s_nop 0
	global_load_lds_dwordx4 v[218:219], off
	s_waitcnt vmcnt(8)
	s_waitcnt lgkmcnt(0)
	s_setprio 1
	s_barrier
	s_waitcnt lgkmcnt(0)
	v_mfma_f32_16x16x32_bf16 v[132:135], v[120:123], v[178:181], v[132:135]
	v_mfma_f32_16x16x32_bf16 v[128:131], v[136:139], v[178:181], v[128:131]
	v_mfma_f32_16x16x32_bf16 v[100:103], v[120:123], v[186:189], v[100:103]
	v_mfma_f32_16x16x32_bf16 v[96:99], v[136:139], v[186:189], v[96:99]
	v_mfma_f32_16x16x32_bf16 v[116:119], v[120:123], v[194:197], v[116:119]
	v_mfma_f32_16x16x32_bf16 v[112:115], v[136:139], v[194:197], v[112:115]
	v_mfma_f32_16x16x32_bf16 v[108:111], v[120:123], v[202:205], v[108:111]
	v_mfma_f32_16x16x32_bf16 v[104:107], v[136:139], v[202:205], v[104:107]
	v_mfma_f32_16x16x32_bf16 v[132:135], v[124:127], v[182:185], v[132:135]
	v_mfma_f32_16x16x32_bf16 v[128:131], v[140:143], v[182:185], v[128:131]
	v_mfma_f32_16x16x32_bf16 v[100:103], v[124:127], v[190:193], v[100:103]
	v_mfma_f32_16x16x32_bf16 v[96:99], v[140:143], v[190:193], v[96:99]
	v_mfma_f32_16x16x32_bf16 v[116:119], v[124:127], v[198:201], v[116:119]
	v_mfma_f32_16x16x32_bf16 v[112:115], v[140:143], v[198:201], v[112:115]
	v_mfma_f32_16x16x32_bf16 v[108:111], v[124:127], v[206:209], v[108:111]
	v_mfma_f32_16x16x32_bf16 v[104:107], v[140:143], v[206:209], v[104:107]
	s_setprio 0
	s_setprio 1
	v_mfma_f32_16x16x32_bf16 v[60:63], v[144:147], v[178:181], v[60:63]
	v_mfma_f32_16x16x32_bf16 v[56:59], v[170:173], v[178:181], v[56:59]
	v_mfma_f32_16x16x32_bf16 v[52:55], v[144:147], v[186:189], v[52:55]
	v_mfma_f32_16x16x32_bf16 v[48:51], v[170:173], v[186:189], v[48:51]
	v_mfma_f32_16x16x32_bf16 v[44:47], v[144:147], v[194:197], v[44:47]
	v_mfma_f32_16x16x32_bf16 v[40:43], v[170:173], v[194:197], v[40:43]
	v_mfma_f32_16x16x32_bf16 v[36:39], v[144:147], v[202:205], v[36:39]
	v_mfma_f32_16x16x32_bf16 v[32:35], v[170:173], v[202:205], v[32:35]
	v_mfma_f32_16x16x32_bf16 v[60:63], v[148:151], v[182:185], v[60:63]
	v_mfma_f32_16x16x32_bf16 v[56:59], v[174:177], v[182:185], v[56:59]
	v_mfma_f32_16x16x32_bf16 v[52:55], v[148:151], v[190:193], v[52:55]
	v_mfma_f32_16x16x32_bf16 v[48:51], v[174:177], v[190:193], v[48:51]
	v_mfma_f32_16x16x32_bf16 v[44:47], v[148:151], v[198:201], v[44:47]
	v_mfma_f32_16x16x32_bf16 v[40:43], v[174:177], v[198:201], v[40:43]
	v_mfma_f32_16x16x32_bf16 v[36:39], v[148:151], v[206:209], v[36:39]
	v_mfma_f32_16x16x32_bf16 v[32:35], v[174:177], v[206:209], v[32:35]
	s_setprio 0
	s_barrier
; #define PG8_STAGE(bufoff, gbase, voff) do { _Pragma("unroll") for (int _i = 0; _i < 2; ++_i) \
;         __builtin_amdgcn_global_load_lds((const unsigned*)((const char*)(gbase) + (voff)[_i]), (LAS unsigned*)(lds + (bufoff) + ldsw + _i * 8192), 16, 0, 0); } while (0)
; #define PG8_LDA(dst, b, h) do { _Pragma("unroll") for (int m = 0; m < 4; ++m) _Pragma("unroll") for (int k = 0; k < 2; ++k) dst[m][k] = *(const LAS bf16x8*)(lds + PG8_SA(b, h) + aoff + m * 2048 + k * 1024); } while (0)
; #define PG8_MMA(ai, bj, At, Bt) do { __builtin_amdgcn_s_setprio(1); _Pragma("unroll") for (int m = 0; m < 4; ++m) _Pragma("unroll") for (int n = 0; n < 2; ++n) _Pragma("unroll") for (int k = 0; k < 2; ++k) \
;         acc[ai][bj][m][n] = __builtin_amdgcn_mfma_f32_16x16x32_bf16(Bt[n][k], At[m][k], acc[ai][bj][m][n], 0, 0, 0); __builtin_amdgcn_s_setprio(0); } while (0)
; #define PG8_WAIT_V(n) asm volatile("s_waitcnt vmcnt(" #n ")" ::: "memory")
; #define PG8_WAIT_L(n) asm volatile("s_waitcnt lgkmcnt(" #n ")" ::: "memory")
; #define PG8_BAR __builtin_amdgcn_s_barrier()
; #define PG8_SCHED __builtin_amdgcn_sched_barrier(0)
; template <class Epi, class Sched, bool ALIGN_EPI = false, bool SP2 = false>
; __device__ __forceinline__ void gemm_phase(LAS unsigned char* lds, const Gemm g, const Sched& S, const Epi& E) {
;     ...
;         for (int t = 0; t < nt; t += 2) {
;     ...
;             PG8_LDA(At, 1, 1); PG8_STAGE(PG8_SB(1, 0), b3, voffB); PG8_STAGE(PG8_SB(1, 1), b3 + hstepB, voffB); PG8_STAGE(PG8_SA(1, 0), a3, voffA);
;             PG8_WAIT_V(8); PG8_WAIT_L(0); PG8_BAR; PG8_MMA(1, 0, At, B0); PG8_MMA(1, 1, At, B1); PG8_BAR; PG8_SCHED;
	s_add_i32 s30, s47, s34
	v_lshl_add_u64 v[210:211], v[210:211], 0, s[10:11]
	s_mov_b32 m0, s30
	ds_read_b128 v[178:181], v223 offset:49152
	ds_read_b128 v[182:185], v223 offset:50176
	ds_read_b128 v[186:189], v223 offset:51200
	ds_read_b128 v[190:193], v223 offset:52224
	ds_read_b128 v[194:197], v223 offset:53248
	ds_read_b128 v[198:201], v223 offset:54272
	ds_read_b128 v[202:205], v223 offset:55296
	ds_read_b128 v[206:209], v223 offset:56320
	global_load_lds_dwordx4 v[210:211], off
	s_add_i32 m0, s30, 0x2000
	s_add_u32 s28, s28, 0x80080
	v_lshl_add_u64 v[210:211], v[212:213], 0, s[10:11]
	s_addc_u32 s29, s29, 0
	s_add_i32 s30, s48, s34
	global_load_lds_dwordx4 v[210:211], off
	v_lshl_add_u64 v[210:211], s[28:29], 0, v[156:157]
	s_mov_b32 m0, s30
	s_nop 0
	global_load_lds_dwordx4 v[210:211], off
	v_lshl_add_u64 v[210:211], s[28:29], 0, v[160:161]
	s_add_i32 m0, s30, 0x2000
	s_nop 0
	global_load_lds_dwordx4 v[210:211], off
	v_lshl_add_u64 v[210:211], v[214:215], 0, s[10:11]
	s_mov_b32 m0, s39
	s_nop 0
	global_load_lds_dwordx4 v[210:211], off
	v_lshl_add_u64 v[210:211], v[216:217], 0, s[10:11]
	s_mov_b32 m0, s40
	s_nop 0
	global_load_lds_dwordx4 v[210:211], off
	s_waitcnt vmcnt(8)
	s_waitcnt lgkmcnt(0)
	s_setprio 1
	s_barrier
	s_waitcnt lgkmcnt(0)
	v_mfma_f32_16x16x32_bf16 v[92:95], v[120:123], v[178:181], v[92:95]
	v_mfma_f32_16x16x32_bf16 v[88:91], v[136:139], v[178:181], v[88:91]
	v_mfma_f32_16x16x32_bf16 v[84:87], v[120:123], v[186:189], v[84:87]
	v_mfma_f32_16x16x32_bf16 v[80:83], v[136:139], v[186:189], v[80:83]
	v_mfma_f32_16x16x32_bf16 v[76:79], v[120:123], v[194:197], v[76:79]
	v_mfma_f32_16x16x32_bf16 v[72:75], v[136:139], v[194:197], v[72:75]
	v_mfma_f32_16x16x32_bf16 v[68:71], v[120:123], v[202:205], v[68:71]
	v_mfma_f32_16x16x32_bf16 v[64:67], v[136:139], v[202:205], v[64:67]
	v_mfma_f32_16x16x32_bf16 v[92:95], v[124:127], v[182:185], v[92:95]
	v_mfma_f32_16x16x32_bf16 v[88:91], v[140:143], v[182:185], v[88:91]
	v_mfma_f32_16x16x32_bf16 v[84:87], v[124:127], v[190:193], v[84:87]
	v_mfma_f32_16x16x32_bf16 v[80:83], v[140:143], v[190:193], v[80:83]
	v_mfma_f32_16x16x32_bf16 v[76:79], v[124:127], v[198:201], v[76:79]
	v_mfma_f32_16x16x32_bf16 v[72:75], v[140:143], v[198:201], v[72:75]
	v_mfma_f32_16x16x32_bf16 v[68:71], v[124:127], v[206:209], v[68:71]
	v_mfma_f32_16x16x32_bf16 v[64:67], v[140:143], v[206:209], v[64:67]
	s_setprio 0
	s_setprio 1
	v_mfma_f32_16x16x32_bf16 v[28:31], v[144:147], v[178:181], v[28:31]
	v_mfma_f32_16x16x32_bf16 v[24:27], v[170:173], v[178:181], v[24:27]
	v_mfma_f32_16x16x32_bf16 v[20:23], v[144:147], v[186:189], v[20:23]
	v_mfma_f32_16x16x32_bf16 v[16:19], v[170:173], v[186:189], v[16:19]
	v_mfma_f32_16x16x32_bf16 v[12:15], v[144:147], v[194:197], v[12:15]
	v_mfma_f32_16x16x32_bf16 v[8:11], v[170:173], v[194:197], v[8:11]
	v_mfma_f32_16x16x32_bf16 v[4:7], v[144:147], v[202:205], v[4:7]
	v_mfma_f32_16x16x32_bf16 v[0:3], v[170:173], v[202:205], v[0:3]
	v_mfma_f32_16x16x32_bf16 v[28:31], v[148:151], v[182:185], v[28:31]
	v_mfma_f32_16x16x32_bf16 v[24:27], v[174:177], v[182:185], v[24:27]
	v_mfma_f32_16x16x32_bf16 v[20:23], v[148:151], v[190:193], v[20:23]
	v_mfma_f32_16x16x32_bf16 v[16:19], v[174:177], v[190:193], v[16:19]
	v_mfma_f32_16x16x32_bf16 v[12:15], v[148:151], v[198:201], v[12:15]
	v_mfma_f32_16x16x32_bf16 v[8:11], v[174:177], v[198:201], v[8:11]
	v_mfma_f32_16x16x32_bf16 v[4:7], v[148:151], v[206:209], v[4:7]
	v_mfma_f32_16x16x32_bf16 v[0:3], v[174:177], v[206:209], v[0:3]
	s_setprio 0
	s_barrier
	s_add_i32 s50, s50, 2
	s_add_u32 s26, s26, 0x100
	s_addc_u32 s27, s27, 0
	s_add_u32 s33, s33, 0x100
	s_addc_u32 s49, s49, 0
	s_cmp_gt_u32 s50, 29
	s_cbranch_scc0 .LBB0_968
	s_and_b64 vcc, exec, s[12:13]
	s_cbranch_vccz .LBB0_971
	s_barrier

; #define PG8_STAGE(bufoff, gbase, voff) do { _Pragma("unroll") for (int _i = 0; _i < 2; ++_i) \
;         __builtin_amdgcn_global_load_lds((const unsigned*)((const char*)(gbase) + (voff)[_i]), (LAS unsigned*)(lds + (bufoff) + ldsw + _i * 8192), 16, 0, 0); } while (0)
; #define PG8_LDA(dst, b, h) do { _Pragma("unroll") for (int m = 0; m < 4; ++m) _Pragma("unroll") for (int k = 0; k < 2; ++k) dst[m][k] = *(const LAS bf16x8*)(lds + PG8_SA(b, h) + aoff + m * 2048 + k * 1024); } while (0)
; #define PG8_LDB(dst, b, h) do { _Pragma("unroll") for (int n = 0; n < 2; ++n) _Pragma("unroll") for (int k = 0; k < 2; ++k) dst[n][k] = *(const LAS bf16x8*)(lds + PG8_SB(b, h) + boff + n * 2048 + k * 1024); } while (0)
; #define PG8_MMA(ai, bj, At, Bt) do { __builtin_amdgcn_s_setprio(1); _Pragma("unroll") for (int m = 0; m < 4; ++m) _Pragma("unroll") for (int n = 0; n < 2; ++n) _Pragma("unroll") for (int k = 0; k < 2; ++k) \
;         acc[ai][bj][m][n] = __builtin_amdgcn_mfma_f32_16x16x32_bf16(Bt[n][k], At[m][k], acc[ai][bj][m][n], 0, 0, 0); __builtin_amdgcn_s_setprio(0); } while (0)
; #define PG8_WAIT_V(n) asm volatile("s_waitcnt vmcnt(" #n ")" ::: "memory")
; #define PG8_WAIT_L(n) asm volatile("s_waitcnt lgkmcnt(" #n ")" ::: "memory")
; #define PG8_BAR __builtin_amdgcn_s_barrier()
; template <class Epi, class Sched, bool ALIGN_EPI = false, bool SP2 = false>
; __device__ __forceinline__ void gemm_phase(LAS unsigned char* lds, const Gemm g, const Sched& S, const Epi& E) {
;     ...
;             const bool last = (t == nt - 2);
;             const char* a1 = cA + (size_t)(t + 1) * kstep;
;             const char* a2 = last ? nA : cA + (size_t)(t + 2) * kstep; const char* b2 = last ? nB : cB + (size_t)(t + 2) * kstep;
;             const char* a3 = a2 + kstep; const char* b3 = b2 + kstep;
;             if (last && has_next) S.a_ready(nxt);
;             if constexpr (SP2) {
;             PG8_LDB(B0, 0, 0); PG8_LDB(B1, 0, 1); PG8_SCHED; PG8_LDA(At, 0, 0); PG8_STAGE(PG8_SA(1, 1), a1 + hstepA, voffA);
;             PG8_WAIT_V(8); PG8_WAIT_L(0); PG8_BAR; PG8_MMA(0, 0, At, B0); PG8_MMA(0, 1, At, B1); PG8_BAR; PG8_SCHED;
;             PG8_LDA(At, 0, 1); PG8_STAGE(PG8_SB(0, 0), b2, voffB); PG8_STAGE(PG8_SB(0, 1), b2 + hstepB, voffB); PG8_STAGE(PG8_SA(0, 0), a2, voffA);
;             PG8_WAIT_V(8); PG8_WAIT_L(0); PG8_BAR; PG8_MMA(1, 0, At, B0); PG8_MMA(1, 1, At, B1); PG8_BAR; PG8_SCHED;
.LBB0_1055:
	ds_read_b128 v[80:83], v171
	ds_read_b128 v[88:91], v171 offset:1024
	ds_read_b128 v[92:95], v171 offset:2048
	ds_read_b128 v[96:99], v171 offset:3072
	ds_read_b128 v[162:165], v172
	ds_read_b128 v[166:169], v172 offset:1024
	ds_read_b128 v[178:181], v172 offset:2048
	ds_read_b128 v[182:185], v172 offset:3072
	s_add_u32 s26, s24, 0xfff80080
	s_addc_u32 s27, s25, -1
	s_cmp_eq_u32 s53, 28
	s_cselect_b32 s29, s17, s27
	s_cselect_b32 s28, s49, s26
	s_cselect_b32 s27, s15, s52
	s_cselect_b32 s26, s50, s51
	v_lshl_add_u64 v[218:219], s[24:25], 0, v[154:155]
	s_add_i32 m0, s23, 0xc000
	ds_read_b128 v[186:189], v173
	ds_read_b128 v[190:193], v173 offset:1024
	ds_read_b128 v[194:197], v173 offset:2048
	ds_read_b128 v[198:201], v173 offset:3072
	ds_read_b128 v[202:205], v173 offset:4096
	ds_read_b128 v[206:209], v173 offset:5120
	ds_read_b128 v[210:213], v173 offset:6144
	ds_read_b128 v[214:217], v173 offset:7168
	global_load_lds_dwordx4 v[218:219], off
	v_lshl_add_u64 v[218:219], s[24:25], 0, v[156:157]
	s_add_i32 m0, s23, 0xe000
	s_nop 0
	global_load_lds_dwordx4 v[218:219], off
	s_waitcnt vmcnt(8)
	s_waitcnt lgkmcnt(0)
	s_setprio 1
	s_barrier
	s_waitcnt lgkmcnt(0)
	v_mfma_f32_16x16x32_bf16 v[140:143], v[80:83], v[186:189], v[140:143]
	v_mfma_f32_16x16x32_bf16 v[136:139], v[92:95], v[186:189], v[136:139]
	v_mfma_f32_16x16x32_bf16 v[124:127], v[80:83], v[194:197], v[124:127]
	v_mfma_f32_16x16x32_bf16 v[120:123], v[92:95], v[194:197], v[120:123]
	v_mfma_f32_16x16x32_bf16 v[108:111], v[80:83], v[202:205], v[108:111]
	v_mfma_f32_16x16x32_bf16 v[104:107], v[92:95], v[202:205], v[104:107]
	v_mfma_f32_16x16x32_bf16 v[76:79], v[80:83], v[210:213], v[76:79]
	v_mfma_f32_16x16x32_bf16 v[72:75], v[92:95], v[210:213], v[72:75]
	v_mfma_f32_16x16x32_bf16 v[140:143], v[88:91], v[190:193], v[140:143]
	v_mfma_f32_16x16x32_bf16 v[136:139], v[96:99], v[190:193], v[136:139]
	v_mfma_f32_16x16x32_bf16 v[124:127], v[88:91], v[198:201], v[124:127]
	v_mfma_f32_16x16x32_bf16 v[120:123], v[96:99], v[198:201], v[120:123]
	v_mfma_f32_16x16x32_bf16 v[108:111], v[88:91], v[206:209], v[108:111]
	v_mfma_f32_16x16x32_bf16 v[104:107], v[96:99], v[206:209], v[104:107]
	v_mfma_f32_16x16x32_bf16 v[76:79], v[88:91], v[214:217], v[76:79]
	v_mfma_f32_16x16x32_bf16 v[72:75], v[96:99], v[214:217], v[72:75]
	s_setprio 0
	s_setprio 1
	v_mfma_f32_16x16x32_bf16 v[132:135], v[162:165], v[186:189], v[132:135]
	v_mfma_f32_16x16x32_bf16 v[128:131], v[178:181], v[186:189], v[128:131]
	v_mfma_f32_16x16x32_bf16 v[116:119], v[162:165], v[194:197], v[116:119]
	v_mfma_f32_16x16x32_bf16 v[112:115], v[178:181], v[194:197], v[112:115]
	v_mfma_f32_16x16x32_bf16 v[100:103], v[162:165], v[202:205], v[100:103]
	v_mfma_f32_16x16x32_bf16 v[84:87], v[178:181], v[202:205], v[84:87]
	v_mfma_f32_16x16x32_bf16 v[68:71], v[162:165], v[210:213], v[68:71]
	v_mfma_f32_16x16x32_bf16 v[64:67], v[178:181], v[210:213], v[64:67]
	v_mfma_f32_16x16x32_bf16 v[132:135], v[166:169], v[190:193], v[132:135]
	v_mfma_f32_16x16x32_bf16 v[128:131], v[182:185], v[190:193], v[128:131]
	v_mfma_f32_16x16x32_bf16 v[116:119], v[166:169], v[198:201], v[116:119]
	v_mfma_f32_16x16x32_bf16 v[112:115], v[182:185], v[198:201], v[112:115]
	v_mfma_f32_16x16x32_bf16 v[100:103], v[166:169], v[206:209], v[100:103]
	v_mfma_f32_16x16x32_bf16 v[84:87], v[182:185], v[206:209], v[84:87]
	v_mfma_f32_16x16x32_bf16 v[68:71], v[166:169], v[214:217], v[68:71]
	v_mfma_f32_16x16x32_bf16 v[64:67], v[182:185], v[214:217], v[64:67]
	s_setprio 0
	s_barrier
	s_add_i32 s54, s43, s30
	v_lshl_add_u64 v[218:219], s[26:27], 0, v[146:147]
	s_mov_b32 m0, s54
	ds_read_b128 v[186:189], v173 offset:16384
	ds_read_b128 v[190:193], v173 offset:17408
	ds_read_b128 v[194:197], v173 offset:18432
	ds_read_b128 v[198:201], v173 offset:19456
	ds_read_b128 v[202:205], v173 offset:20480
	ds_read_b128 v[206:209], v173 offset:21504
	ds_read_b128 v[210:213], v173 offset:22528
	ds_read_b128 v[214:217], v173 offset:23552
	global_load_lds_dwordx4 v[218:219], off
	s_add_i32 m0, s54, 0x2000
	s_add_u32 s54, s26, 0x80000
	v_lshl_add_u64 v[220:221], s[26:27], 0, v[150:151]
	s_addc_u32 s55, s27, 0
	s_add_i32 s56, s44, s30
	global_load_lds_dwordx4 v[220:221], off
	v_lshl_add_u64 v[222:223], s[54:55], 0, v[146:147]
	s_mov_b32 m0, s56
	v_lshl_add_u64 v[224:225], s[28:29], 0, v[148:149]
	global_load_lds_dwordx4 v[222:223], off
	v_lshl_add_u64 v[222:223], s[54:55], 0, v[150:151]
	s_add_i32 m0, s56, 0x2000
	s_nop 0
	global_load_lds_dwordx4 v[222:223], off
	v_lshl_add_u64 v[222:223], s[28:29], 0, v[144:145]
	s_mov_b32 m0, s23
	s_nop 0
	global_load_lds_dwordx4 v[222:223], off
	s_mov_b32 m0, s35
	s_nop 0
	global_load_lds_dwordx4 v[224:225], off
	s_waitcnt vmcnt(8)
	s_waitcnt lgkmcnt(0)
	s_setprio 1
	s_barrier
; #define PG8_STAGE(bufoff, gbase, voff) do { _Pragma("unroll") for (int _i = 0; _i < 2; ++_i) \
;         __builtin_amdgcn_global_load_lds((const unsigned*)((const char*)(gbase) + (voff)[_i]), (LAS unsigned*)(lds + (bufoff) + ldsw + _i * 8192), 16, 0, 0); } while (0)
; #define PG8_LDA(dst, b, h) do { _Pragma("unroll") for (int m = 0; m < 4; ++m) _Pragma("unroll") for (int k = 0; k < 2; ++k) dst[m][k] = *(const LAS bf16x8*)(lds + PG8_SA(b, h) + aoff + m * 2048 + k * 1024); } while (0)
; #define PG8_LDB(dst, b, h) do { _Pragma("unroll") for (int n = 0; n < 2; ++n) _Pragma("unroll") for (int k = 0; k < 2; ++k) dst[n][k] = *(const LAS bf16x8*)(lds + PG8_SB(b, h) + boff + n * 2048 + k * 1024); } while (0)
; #define PG8_MMA(ai, bj, At, Bt) do { __builtin_amdgcn_s_setprio(1); _Pragma("unroll") for (int m = 0; m < 4; ++m) _Pragma("unroll") for (int n = 0; n < 2; ++n) _Pragma("unroll") for (int k = 0; k < 2; ++k) \
;         acc[ai][bj][m][n] = __builtin_amdgcn_mfma_f32_16x16x32_bf16(Bt[n][k], At[m][k], acc[ai][bj][m][n], 0, 0, 0); __builtin_amdgcn_s_setprio(0); } while (0)
; #define PG8_WAIT_V(n) asm volatile("s_waitcnt vmcnt(" #n ")" ::: "memory")
; #define PG8_WAIT_L(n) asm volatile("s_waitcnt lgkmcnt(" #n ")" ::: "memory")
; #define PG8_BAR __builtin_amdgcn_s_barrier()
; #define PG8_SCHED __builtin_amdgcn_sched_barrier(0)
; template <class Epi, class Sched, bool ALIGN_EPI = false, bool SP2 = false>
; __device__ __forceinline__ void gemm_phase(LAS unsigned char* lds, const Gemm g, const Sched& S, const Epi& E) {
;     ...
;             PG8_WAIT_V(8); PG8_WAIT_L(0); PG8_BAR; PG8_MMA(1, 0, At, B0); PG8_MMA(1, 1, At, B1); PG8_BAR; PG8_SCHED;
;             PG8_LDB(B0, 1, 0); PG8_LDB(B1, 1, 1); PG8_SCHED; PG8_LDA(At, 1, 0); PG8_STAGE(PG8_SA(0, 1), a2 + hstepA, voffA);
;             PG8_WAIT_V(8); PG8_WAIT_L(0); PG8_BAR; PG8_MMA(0, 0, At, B0); PG8_MMA(0, 1, At, B1); PG8_BAR; PG8_SCHED;
	s_waitcnt lgkmcnt(0)
	v_mfma_f32_16x16x32_bf16 v[60:63], v[80:83], v[186:189], v[60:63]
	v_mfma_f32_16x16x32_bf16 v[56:59], v[92:95], v[186:189], v[56:59]
	v_mfma_f32_16x16x32_bf16 v[44:47], v[80:83], v[194:197], v[44:47]
	v_mfma_f32_16x16x32_bf16 v[40:43], v[92:95], v[194:197], v[40:43]
	v_mfma_f32_16x16x32_bf16 v[28:31], v[80:83], v[202:205], v[28:31]
	v_mfma_f32_16x16x32_bf16 v[24:27], v[92:95], v[202:205], v[24:27]
	v_mfma_f32_16x16x32_bf16 v[12:15], v[80:83], v[210:213], v[12:15]
	v_mfma_f32_16x16x32_bf16 v[8:11], v[92:95], v[210:213], v[8:11]
	v_mfma_f32_16x16x32_bf16 v[60:63], v[88:91], v[190:193], v[60:63]
	v_mfma_f32_16x16x32_bf16 v[56:59], v[96:99], v[190:193], v[56:59]
	v_mfma_f32_16x16x32_bf16 v[44:47], v[88:91], v[198:201], v[44:47]
	v_mfma_f32_16x16x32_bf16 v[40:43], v[96:99], v[198:201], v[40:43]
	v_mfma_f32_16x16x32_bf16 v[28:31], v[88:91], v[206:209], v[28:31]
	v_mfma_f32_16x16x32_bf16 v[24:27], v[96:99], v[206:209], v[24:27]
	v_mfma_f32_16x16x32_bf16 v[12:15], v[88:91], v[214:217], v[12:15]
	v_mfma_f32_16x16x32_bf16 v[8:11], v[96:99], v[214:217], v[8:11]
	s_setprio 0
	s_setprio 1
	v_mfma_f32_16x16x32_bf16 v[52:55], v[162:165], v[186:189], v[52:55]
	v_mfma_f32_16x16x32_bf16 v[48:51], v[178:181], v[186:189], v[48:51]
	v_mfma_f32_16x16x32_bf16 v[36:39], v[162:165], v[194:197], v[36:39]
	v_mfma_f32_16x16x32_bf16 v[32:35], v[178:181], v[194:197], v[32:35]
	v_mfma_f32_16x16x32_bf16 v[20:23], v[162:165], v[202:205], v[20:23]
	v_mfma_f32_16x16x32_bf16 v[16:19], v[178:181], v[202:205], v[16:19]
	v_mfma_f32_16x16x32_bf16 v[4:7], v[162:165], v[210:213], v[4:7]
	v_mfma_f32_16x16x32_bf16 v[0:3], v[178:181], v[210:213], v[0:3]
	v_mfma_f32_16x16x32_bf16 v[52:55], v[166:169], v[190:193], v[52:55]
	v_mfma_f32_16x16x32_bf16 v[48:51], v[182:185], v[190:193], v[48:51]
	v_mfma_f32_16x16x32_bf16 v[36:39], v[166:169], v[198:201], v[36:39]
	v_mfma_f32_16x16x32_bf16 v[32:35], v[182:185], v[198:201], v[32:35]
	v_mfma_f32_16x16x32_bf16 v[20:23], v[166:169], v[206:209], v[20:23]
	v_mfma_f32_16x16x32_bf16 v[16:19], v[182:185], v[206:209], v[16:19]
	v_mfma_f32_16x16x32_bf16 v[4:7], v[166:169], v[214:217], v[4:7]
	v_mfma_f32_16x16x32_bf16 v[0:3], v[182:185], v[214:217], v[0:3]
	s_setprio 0
	s_barrier
	ds_read_b128 v[80:83], v175
	ds_read_b128 v[88:91], v175 offset:1024
	ds_read_b128 v[92:95], v175 offset:2048
	ds_read_b128 v[96:99], v175 offset:3072
	ds_read_b128 v[162:165], v176
	ds_read_b128 v[166:169], v176 offset:1024
	ds_read_b128 v[178:181], v176 offset:2048
	ds_read_b128 v[182:185], v176 offset:3072
	s_add_u32 s28, s28, 0x80000
	s_addc_u32 s29, s29, 0
	s_mov_b32 m0, s36
	v_lshl_add_u64 v[226:227], s[28:29], 0, v[144:145]
	ds_read_b128 v[186:189], v173 offset:32768
	ds_read_b128 v[190:193], v173 offset:33792
	ds_read_b128 v[194:197], v173 offset:34816
	ds_read_b128 v[198:201], v173 offset:35840
	ds_read_b128 v[202:205], v173 offset:36864
	ds_read_b128 v[206:209], v173 offset:37888
	ds_read_b128 v[210:213], v173 offset:38912
	ds_read_b128 v[214:217], v173 offset:39936
	global_load_lds_dwordx4 v[226:227], off
	v_lshl_add_u64 v[226:227], s[28:29], 0, v[148:149]
	s_mov_b32 m0, s37
	s_nop 0
	global_load_lds_dwordx4 v[226:227], off
	s_waitcnt vmcnt(8)
	s_waitcnt lgkmcnt(0)
	s_setprio 1
	s_barrier
	s_waitcnt lgkmcnt(0)
	v_mfma_f32_16x16x32_bf16 v[140:143], v[80:83], v[186:189], v[140:143]
	v_mfma_f32_16x16x32_bf16 v[136:139], v[92:95], v[186:189], v[136:139]
	v_mfma_f32_16x16x32_bf16 v[124:127], v[80:83], v[194:197], v[124:127]
	v_mfma_f32_16x16x32_bf16 v[120:123], v[92:95], v[194:197], v[120:123]
	v_mfma_f32_16x16x32_bf16 v[108:111], v[80:83], v[202:205], v[108:111]
	v_mfma_f32_16x16x32_bf16 v[104:107], v[92:95], v[202:205], v[104:107]
	v_mfma_f32_16x16x32_bf16 v[76:79], v[80:83], v[210:213], v[76:79]
	v_mfma_f32_16x16x32_bf16 v[72:75], v[92:95], v[210:213], v[72:75]
	v_mfma_f32_16x16x32_bf16 v[140:143], v[88:91], v[190:193], v[140:143]
	v_mfma_f32_16x16x32_bf16 v[136:139], v[96:99], v[190:193], v[136:139]
	v_mfma_f32_16x16x32_bf16 v[124:127], v[88:91], v[198:201], v[124:127]
	v_mfma_f32_16x16x32_bf16 v[120:123], v[96:99], v[198:201], v[120:123]
	v_mfma_f32_16x16x32_bf16 v[108:111], v[88:91], v[206:209], v[108:111]
	v_mfma_f32_16x16x32_bf16 v[104:107], v[96:99], v[206:209], v[104:107]
	v_mfma_f32_16x16x32_bf16 v[76:79], v[88:91], v[214:217], v[76:79]
	v_mfma_f32_16x16x32_bf16 v[72:75], v[96:99], v[214:217], v[72:75]
	s_setprio 0
	s_setprio 1
	v_mfma_f32_16x16x32_bf16 v[132:135], v[162:165], v[186:189], v[132:135]
	v_mfma_f32_16x16x32_bf16 v[128:131], v[178:181], v[186:189], v[128:131]
	v_mfma_f32_16x16x32_bf16 v[116:119], v[162:165], v[194:197], v[116:119]
	v_mfma_f32_16x16x32_bf16 v[112:115], v[178:181], v[194:197], v[112:115]
	v_mfma_f32_16x16x32_bf16 v[100:103], v[162:165], v[202:205], v[100:103]
	v_mfma_f32_16x16x32_bf16 v[84:87], v[178:181], v[202:205], v[84:87]
	v_mfma_f32_16x16x32_bf16 v[68:71], v[162:165], v[210:213], v[68:71]
	v_mfma_f32_16x16x32_bf16 v[64:67], v[178:181], v[210:213], v[64:67]
	v_mfma_f32_16x16x32_bf16 v[132:135], v[166:169], v[190:193], v[132:135]
	v_mfma_f32_16x16x32_bf16 v[128:131], v[182:185], v[190:193], v[128:131]
	v_mfma_f32_16x16x32_bf16 v[116:119], v[166:169], v[198:201], v[116:119]
	v_mfma_f32_16x16x32_bf16 v[112:115], v[182:185], v[198:201], v[112:115]
	v_mfma_f32_16x16x32_bf16 v[100:103], v[166:169], v[206:209], v[100:103]
	v_mfma_f32_16x16x32_bf16 v[84:87], v[182:185], v[206:209], v[84:87]
	v_mfma_f32_16x16x32_bf16 v[68:71], v[166:169], v[214:217], v[68:71]
	v_mfma_f32_16x16x32_bf16 v[64:67], v[182:185], v[214:217], v[64:67]
	s_setprio 0
	s_barrier
; #define PG8_STAGE(bufoff, gbase, voff) do { _Pragma("unroll") for (int _i = 0; _i < 2; ++_i) \
;         __builtin_amdgcn_global_load_lds((const unsigned*)((const char*)(gbase) + (voff)[_i]), (LAS unsigned*)(lds + (bufoff) + ldsw + _i * 8192), 16, 0, 0); } while (0)
; #define PG8_LDA(dst, b, h) do { _Pragma("unroll") for (int m = 0; m < 4; ++m) _Pragma("unroll") for (int k = 0; k < 2; ++k) dst[m][k] = *(const LAS bf16x8*)(lds + PG8_SA(b, h) + aoff + m * 2048 + k * 1024); } while (0)
; #define PG8_MMA(ai, bj, At, Bt) do { __builtin_amdgcn_s_setprio(1); _Pragma("unroll") for (int m = 0; m < 4; ++m) _Pragma("unroll") for (int n = 0; n < 2; ++n) _Pragma("unroll") for (int k = 0; k < 2; ++k) \
;         acc[ai][bj][m][n] = __builtin_amdgcn_mfma_f32_16x16x32_bf16(Bt[n][k], At[m][k], acc[ai][bj][m][n], 0, 0, 0); __builtin_amdgcn_s_setprio(0); } while (0)
; #define PG8_WAIT_V(n) asm volatile("s_waitcnt vmcnt(" #n ")" ::: "memory")
; #define PG8_WAIT_L(n) asm volatile("s_waitcnt lgkmcnt(" #n ")" ::: "memory")
; #define PG8_BAR __builtin_amdgcn_s_barrier()
; #define PG8_SCHED __builtin_amdgcn_sched_barrier(0)
; template <class Epi, class Sched, bool ALIGN_EPI = false, bool SP2 = false>
; __device__ __forceinline__ void gemm_phase(LAS unsigned char* lds, const Gemm g, const Sched& S, const Epi& E) {
;     ...
;         for (int t = 0; t < nt; t += 2) {
;     ...
;             PG8_LDA(At, 1, 1); PG8_STAGE(PG8_SB(1, 0), b3, voffB); PG8_STAGE(PG8_SB(1, 1), b3 + hstepB, voffB); PG8_STAGE(PG8_SA(1, 0), a3, voffA);
;             PG8_WAIT_V(8); PG8_WAIT_L(0); PG8_BAR; PG8_MMA(1, 0, At, B0); PG8_MMA(1, 1, At, B1); PG8_BAR; PG8_SCHED;
	s_add_i32 s28, s47, s30
	v_lshl_add_u64 v[218:219], v[218:219], 0, s[8:9]
	s_mov_b32 m0, s28
	ds_read_b128 v[186:189], v173 offset:49152
	ds_read_b128 v[190:193], v173 offset:50176
	ds_read_b128 v[194:197], v173 offset:51200
	ds_read_b128 v[198:201], v173 offset:52224
	ds_read_b128 v[202:205], v173 offset:53248
	ds_read_b128 v[206:209], v173 offset:54272
	ds_read_b128 v[210:213], v173 offset:55296
	ds_read_b128 v[214:217], v173 offset:56320
	global_load_lds_dwordx4 v[218:219], off
	s_add_i32 m0, s28, 0x2000
	s_add_u32 s26, s26, 0x80080
	v_lshl_add_u64 v[218:219], v[220:221], 0, s[8:9]
	s_addc_u32 s27, s27, 0
	s_add_i32 s28, s48, s30
	global_load_lds_dwordx4 v[218:219], off
	v_lshl_add_u64 v[218:219], s[26:27], 0, v[146:147]
	s_mov_b32 m0, s28
	s_nop 0
	global_load_lds_dwordx4 v[218:219], off
	v_lshl_add_u64 v[218:219], s[26:27], 0, v[150:151]
	s_add_i32 m0, s28, 0x2000
	s_nop 0
	global_load_lds_dwordx4 v[218:219], off
	v_lshl_add_u64 v[218:219], v[222:223], 0, s[8:9]
	s_mov_b32 m0, s40
	s_nop 0
	global_load_lds_dwordx4 v[218:219], off
	v_lshl_add_u64 v[218:219], v[224:225], 0, s[8:9]
	s_mov_b32 m0, s41
	s_nop 0
	global_load_lds_dwordx4 v[218:219], off
	s_waitcnt vmcnt(8)
	s_waitcnt lgkmcnt(0)
	s_setprio 1
	s_barrier
	s_waitcnt lgkmcnt(0)
	v_mfma_f32_16x16x32_bf16 v[60:63], v[80:83], v[186:189], v[60:63]
	v_mfma_f32_16x16x32_bf16 v[56:59], v[92:95], v[186:189], v[56:59]
	v_mfma_f32_16x16x32_bf16 v[44:47], v[80:83], v[194:197], v[44:47]
	v_mfma_f32_16x16x32_bf16 v[40:43], v[92:95], v[194:197], v[40:43]
	v_mfma_f32_16x16x32_bf16 v[28:31], v[80:83], v[202:205], v[28:31]
	v_mfma_f32_16x16x32_bf16 v[24:27], v[92:95], v[202:205], v[24:27]
	v_mfma_f32_16x16x32_bf16 v[12:15], v[80:83], v[210:213], v[12:15]
	v_mfma_f32_16x16x32_bf16 v[8:11], v[92:95], v[210:213], v[8:11]
	v_mfma_f32_16x16x32_bf16 v[60:63], v[88:91], v[190:193], v[60:63]
	v_mfma_f32_16x16x32_bf16 v[56:59], v[96:99], v[190:193], v[56:59]
	v_mfma_f32_16x16x32_bf16 v[44:47], v[88:91], v[198:201], v[44:47]
	v_mfma_f32_16x16x32_bf16 v[40:43], v[96:99], v[198:201], v[40:43]
	v_mfma_f32_16x16x32_bf16 v[28:31], v[88:91], v[206:209], v[28:31]
	v_mfma_f32_16x16x32_bf16 v[24:27], v[96:99], v[206:209], v[24:27]
	v_mfma_f32_16x16x32_bf16 v[12:15], v[88:91], v[214:217], v[12:15]
	v_mfma_f32_16x16x32_bf16 v[8:11], v[96:99], v[214:217], v[8:11]
	s_setprio 0
	s_setprio 1
	v_mfma_f32_16x16x32_bf16 v[52:55], v[162:165], v[186:189], v[52:55]
	v_mfma_f32_16x16x32_bf16 v[48:51], v[178:181], v[186:189], v[48:51]
	v_mfma_f32_16x16x32_bf16 v[36:39], v[162:165], v[194:197], v[36:39]
	v_mfma_f32_16x16x32_bf16 v[32:35], v[178:181], v[194:197], v[32:35]
	v_mfma_f32_16x16x32_bf16 v[20:23], v[162:165], v[202:205], v[20:23]
	v_mfma_f32_16x16x32_bf16 v[16:19], v[178:181], v[202:205], v[16:19]
	v_mfma_f32_16x16x32_bf16 v[4:7], v[162:165], v[210:213], v[4:7]
	v_mfma_f32_16x16x32_bf16 v[0:3], v[178:181], v[210:213], v[0:3]
	v_mfma_f32_16x16x32_bf16 v[52:55], v[166:169], v[190:193], v[52:55]
	v_mfma_f32_16x16x32_bf16 v[48:51], v[182:185], v[190:193], v[48:51]
	v_mfma_f32_16x16x32_bf16 v[36:39], v[166:169], v[198:201], v[36:39]
	v_mfma_f32_16x16x32_bf16 v[32:35], v[182:185], v[198:201], v[32:35]
	v_mfma_f32_16x16x32_bf16 v[20:23], v[166:169], v[206:209], v[20:23]
	v_mfma_f32_16x16x32_bf16 v[16:19], v[182:185], v[206:209], v[16:19]
	v_mfma_f32_16x16x32_bf16 v[4:7], v[166:169], v[214:217], v[4:7]
	v_mfma_f32_16x16x32_bf16 v[0:3], v[182:185], v[214:217], v[0:3]
	s_setprio 0
	s_barrier
	s_add_i32 s53, s53, 2
	s_add_u32 s24, s24, 0x100
	s_addc_u32 s25, s25, 0
	s_add_u32 s51, s51, 0x100
	s_addc_u32 s52, s52, 0
	s_cmp_gt_u32 s53, 29
	s_cbranch_scc0 .LBB0_1055
	s_and_b64 vcc, exec, s[10:11]
	s_cbranch_vccz .LBB0_1058
	s_barrier

; #define PG8_STAGE(bufoff, gbase, voff) do { _Pragma("unroll") for (int _i = 0; _i < 2; ++_i) \
;         __builtin_amdgcn_global_load_lds((const unsigned*)((const char*)(gbase) + (voff)[_i]), (LAS unsigned*)(lds + (bufoff) + ldsw + _i * 8192), 16, 0, 0); } while (0)
; #define PG8_LDA(dst, b, h) do { _Pragma("unroll") for (int m = 0; m < 4; ++m) _Pragma("unroll") for (int k = 0; k < 2; ++k) dst[m][k] = *(const LAS bf16x8*)(lds + PG8_SA(b, h) + aoff + m * 2048 + k * 1024); } while (0)
; #define PG8_LDB(dst, b, h) do { _Pragma("unroll") for (int n = 0; n < 2; ++n) _Pragma("unroll") for (int k = 0; k < 2; ++k) dst[n][k] = *(const LAS bf16x8*)(lds + PG8_SB(b, h) + boff + n * 2048 + k * 1024); } while (0)
; #define PG8_MMA(ai, bj, At, Bt) do { __builtin_amdgcn_s_setprio(1); _Pragma("unroll") for (int m = 0; m < 4; ++m) _Pragma("unroll") for (int n = 0; n < 2; ++n) _Pragma("unroll") for (int k = 0; k < 2; ++k) \
;         acc[ai][bj][m][n] = __builtin_amdgcn_mfma_f32_16x16x32_bf16(Bt[n][k], At[m][k], acc[ai][bj][m][n], 0, 0, 0); __builtin_amdgcn_s_setprio(0); } while (0)
; #define PG8_WAIT_V(n) asm volatile("s_waitcnt vmcnt(" #n ")" ::: "memory")
; #define PG8_WAIT_L(n) asm volatile("s_waitcnt lgkmcnt(" #n ")" ::: "memory")
; #define PG8_BAR __builtin_amdgcn_s_barrier()
; template <class Epi, class Sched, bool ALIGN_EPI = false, bool SP2 = false>
; __device__ __forceinline__ void gemm_phase(LAS unsigned char* lds, const Gemm g, const Sched& S, const Epi& E) {
;     ...
;             const bool last = (t == nt - 2);
;             const char* a1 = cA + (size_t)(t + 1) * kstep;
;             const char* a2 = last ? nA : cA + (size_t)(t + 2) * kstep; const char* b2 = last ? nB : cB + (size_t)(t + 2) * kstep;
;             const char* a3 = a2 + kstep; const char* b3 = b2 + kstep;
;             if (last && has_next) S.a_ready(nxt);
;             if constexpr (SP2) {
;             PG8_LDB(B0, 0, 0); PG8_LDB(B1, 0, 1); PG8_SCHED; PG8_LDA(At, 0, 0); PG8_STAGE(PG8_SA(1, 1), a1 + hstepA, voffA);
;             PG8_WAIT_V(8); PG8_WAIT_L(0); PG8_BAR; PG8_MMA(0, 0, At, B0); PG8_MMA(0, 1, At, B1); PG8_BAR; PG8_SCHED;
;             PG8_LDA(At, 0, 1); PG8_STAGE(PG8_SB(0, 0), b2, voffB); PG8_STAGE(PG8_SB(0, 1), b2 + hstepB, voffB); PG8_STAGE(PG8_SA(0, 0), a2, voffA);
;             PG8_WAIT_V(8); PG8_WAIT_L(0); PG8_BAR; PG8_MMA(1, 0, At, B0); PG8_MMA(1, 1, At, B1); PG8_BAR; PG8_SCHED;
.LBB0_1138:
	ds_read_b128 v[128:131], v176
	ds_read_b128 v[132:135], v176 offset:1024
	ds_read_b128 v[152:155], v176 offset:2048
	ds_read_b128 v[156:159], v176 offset:3072
	ds_read_b128 v[160:163], v177
	ds_read_b128 v[164:167], v177 offset:1024
	ds_read_b128 v[168:171], v177 offset:2048
	ds_read_b128 v[182:185], v177 offset:3072
	s_add_u32 s22, s20, 0xffea0080
	s_addc_u32 s23, s21, -1
	s_cmpk_eq_i32 s49, 0x54
	s_cselect_b32 s25, s3, s23
	s_cselect_b32 s24, s2, s22
	s_cselect_b32 s23, s19, s48
	s_cselect_b32 s22, s18, s47
	v_lshl_add_u64 v[172:173], s[20:21], 0, v[144:145]
	s_add_i32 m0, s28, 0xc000
	ds_read_b128 v[186:189], v178
	ds_read_b128 v[190:193], v178 offset:1024
	ds_read_b128 v[194:197], v178 offset:2048
	ds_read_b128 v[198:201], v178 offset:3072
	ds_read_b128 v[202:205], v178 offset:4096
	ds_read_b128 v[206:209], v178 offset:5120
	ds_read_b128 v[210:213], v178 offset:6144
	ds_read_b128 v[214:217], v178 offset:7168
	global_load_lds_dwordx4 v[172:173], off
	v_lshl_add_u64 v[172:173], s[20:21], 0, v[146:147]
	s_add_i32 m0, s28, 0xe000
	s_nop 0
	global_load_lds_dwordx4 v[172:173], off
	s_waitcnt vmcnt(8)
	s_waitcnt lgkmcnt(0)
	s_setprio 1
	s_barrier
	s_waitcnt lgkmcnt(0)
	v_mfma_f32_16x16x32_bf16 v[124:127], v[128:131], v[186:189], v[124:127]
	v_mfma_f32_16x16x32_bf16 v[120:123], v[152:155], v[186:189], v[120:123]
	v_mfma_f32_16x16x32_bf16 v[116:119], v[128:131], v[194:197], v[116:119]
	v_mfma_f32_16x16x32_bf16 v[112:115], v[152:155], v[194:197], v[112:115]
	v_mfma_f32_16x16x32_bf16 v[108:111], v[128:131], v[202:205], v[108:111]
	v_mfma_f32_16x16x32_bf16 v[104:107], v[152:155], v[202:205], v[104:107]
	v_mfma_f32_16x16x32_bf16 v[100:103], v[128:131], v[210:213], v[100:103]
	v_mfma_f32_16x16x32_bf16 v[96:99], v[152:155], v[210:213], v[96:99]
	v_mfma_f32_16x16x32_bf16 v[124:127], v[132:135], v[190:193], v[124:127]
	v_mfma_f32_16x16x32_bf16 v[120:123], v[156:159], v[190:193], v[120:123]
	v_mfma_f32_16x16x32_bf16 v[116:119], v[132:135], v[198:201], v[116:119]
	v_mfma_f32_16x16x32_bf16 v[112:115], v[156:159], v[198:201], v[112:115]
	v_mfma_f32_16x16x32_bf16 v[108:111], v[132:135], v[206:209], v[108:111]
	v_mfma_f32_16x16x32_bf16 v[104:107], v[156:159], v[206:209], v[104:107]
	v_mfma_f32_16x16x32_bf16 v[100:103], v[132:135], v[214:217], v[100:103]
	v_mfma_f32_16x16x32_bf16 v[96:99], v[156:159], v[214:217], v[96:99]
	s_setprio 0
	s_setprio 1
	v_mfma_f32_16x16x32_bf16 v[68:71], v[160:163], v[186:189], v[68:71]
	v_mfma_f32_16x16x32_bf16 v[60:63], v[168:171], v[186:189], v[60:63]
	v_mfma_f32_16x16x32_bf16 v[52:55], v[160:163], v[194:197], v[52:55]
	v_mfma_f32_16x16x32_bf16 v[48:51], v[168:171], v[194:197], v[48:51]
	v_mfma_f32_16x16x32_bf16 v[44:47], v[160:163], v[202:205], v[44:47]
	v_mfma_f32_16x16x32_bf16 v[40:43], v[168:171], v[202:205], v[40:43]
	v_mfma_f32_16x16x32_bf16 v[36:39], v[160:163], v[210:213], v[36:39]
	v_mfma_f32_16x16x32_bf16 v[32:35], v[168:171], v[210:213], v[32:35]
	v_mfma_f32_16x16x32_bf16 v[68:71], v[164:167], v[190:193], v[68:71]
	v_mfma_f32_16x16x32_bf16 v[60:63], v[182:185], v[190:193], v[60:63]
	v_mfma_f32_16x16x32_bf16 v[52:55], v[164:167], v[198:201], v[52:55]
	v_mfma_f32_16x16x32_bf16 v[48:51], v[182:185], v[198:201], v[48:51]
	v_mfma_f32_16x16x32_bf16 v[44:47], v[164:167], v[206:209], v[44:47]
	v_mfma_f32_16x16x32_bf16 v[40:43], v[182:185], v[206:209], v[40:43]
	v_mfma_f32_16x16x32_bf16 v[36:39], v[164:167], v[214:217], v[36:39]
	v_mfma_f32_16x16x32_bf16 v[32:35], v[182:185], v[214:217], v[32:35]
	s_setprio 0
	s_barrier
	s_add_i32 s50, s40, s27
	v_lshl_add_u64 v[172:173], s[22:23], 0, v[138:139]
	s_mov_b32 m0, s50
	ds_read_b128 v[186:189], v178 offset:16384
	ds_read_b128 v[190:193], v178 offset:17408
	ds_read_b128 v[194:197], v178 offset:18432
	ds_read_b128 v[198:201], v178 offset:19456
	ds_read_b128 v[202:205], v178 offset:20480
	ds_read_b128 v[206:209], v178 offset:21504
	ds_read_b128 v[210:213], v178 offset:22528
	ds_read_b128 v[214:217], v178 offset:23552
	global_load_lds_dwordx4 v[172:173], off
	s_add_i32 m0, s50, 0x2000
	s_add_u32 s50, s22, 0x160000
	v_lshl_add_u64 v[218:219], s[22:23], 0, v[142:143]
	s_addc_u32 s51, s23, 0
	s_add_i32 s52, s41, s27
	global_load_lds_dwordx4 v[218:219], off
	v_lshl_add_u64 v[220:221], s[50:51], 0, v[138:139]
	s_mov_b32 m0, s52
	v_lshl_add_u64 v[222:223], s[24:25], 0, v[140:141]
	global_load_lds_dwordx4 v[220:221], off
	v_lshl_add_u64 v[220:221], s[50:51], 0, v[142:143]
	s_add_i32 m0, s52, 0x2000
	s_nop 0
	global_load_lds_dwordx4 v[220:221], off
	v_lshl_add_u64 v[220:221], s[24:25], 0, v[136:137]
	s_mov_b32 m0, s28
	s_nop 0
	global_load_lds_dwordx4 v[220:221], off
	s_mov_b32 m0, s29
	s_nop 0
	global_load_lds_dwordx4 v[222:223], off
	s_waitcnt vmcnt(8)
	s_waitcnt lgkmcnt(0)
	s_setprio 1
	s_barrier
; #define PG8_STAGE(bufoff, gbase, voff) do { _Pragma("unroll") for (int _i = 0; _i < 2; ++_i) \
;         __builtin_amdgcn_global_load_lds((const unsigned*)((const char*)(gbase) + (voff)[_i]), (LAS unsigned*)(lds + (bufoff) + ldsw + _i * 8192), 16, 0, 0); } while (0)
; #define PG8_LDA(dst, b, h) do { _Pragma("unroll") for (int m = 0; m < 4; ++m) _Pragma("unroll") for (int k = 0; k < 2; ++k) dst[m][k] = *(const LAS bf16x8*)(lds + PG8_SA(b, h) + aoff + m * 2048 + k * 1024); } while (0)
; #define PG8_LDB(dst, b, h) do { _Pragma("unroll") for (int n = 0; n < 2; ++n) _Pragma("unroll") for (int k = 0; k < 2; ++k) dst[n][k] = *(const LAS bf16x8*)(lds + PG8_SB(b, h) + boff + n * 2048 + k * 1024); } while (0)
; #define PG8_MMA(ai, bj, At, Bt) do { __builtin_amdgcn_s_setprio(1); _Pragma("unroll") for (int m = 0; m < 4; ++m) _Pragma("unroll") for (int n = 0; n < 2; ++n) _Pragma("unroll") for (int k = 0; k < 2; ++k) \
;         acc[ai][bj][m][n] = __builtin_amdgcn_mfma_f32_16x16x32_bf16(Bt[n][k], At[m][k], acc[ai][bj][m][n], 0, 0, 0); __builtin_amdgcn_s_setprio(0); } while (0)
; #define PG8_WAIT_V(n) asm volatile("s_waitcnt vmcnt(" #n ")" ::: "memory")
; #define PG8_WAIT_L(n) asm volatile("s_waitcnt lgkmcnt(" #n ")" ::: "memory")
; #define PG8_BAR __builtin_amdgcn_s_barrier()
; #define PG8_SCHED __builtin_amdgcn_sched_barrier(0)
; template <class Epi, class Sched, bool ALIGN_EPI = false, bool SP2 = false>
; __device__ __forceinline__ void gemm_phase(LAS unsigned char* lds, const Gemm g, const Sched& S, const Epi& E) {
;     ...
;             PG8_WAIT_V(8); PG8_WAIT_L(0); PG8_BAR; PG8_MMA(1, 0, At, B0); PG8_MMA(1, 1, At, B1); PG8_BAR; PG8_SCHED;
;             PG8_LDB(B0, 1, 0); PG8_LDB(B1, 1, 1); PG8_SCHED; PG8_LDA(At, 1, 0); PG8_STAGE(PG8_SA(0, 1), a2 + hstepA, voffA);
;             PG8_WAIT_V(8); PG8_WAIT_L(0); PG8_BAR; PG8_MMA(0, 0, At, B0); PG8_MMA(0, 1, At, B1); PG8_BAR; PG8_SCHED;
	s_waitcnt lgkmcnt(0)
	v_mfma_f32_16x16x32_bf16 v[92:95], v[128:131], v[186:189], v[92:95]
	v_mfma_f32_16x16x32_bf16 v[88:91], v[152:155], v[186:189], v[88:91]
	v_mfma_f32_16x16x32_bf16 v[84:87], v[128:131], v[194:197], v[84:87]
	v_mfma_f32_16x16x32_bf16 v[80:83], v[152:155], v[194:197], v[80:83]
	v_mfma_f32_16x16x32_bf16 v[76:79], v[128:131], v[202:205], v[76:79]
	v_mfma_f32_16x16x32_bf16 v[72:75], v[152:155], v[202:205], v[72:75]
	v_mfma_f32_16x16x32_bf16 v[64:67], v[128:131], v[210:213], v[64:67]
	v_mfma_f32_16x16x32_bf16 v[56:59], v[152:155], v[210:213], v[56:59]
	v_mfma_f32_16x16x32_bf16 v[92:95], v[132:135], v[190:193], v[92:95]
	v_mfma_f32_16x16x32_bf16 v[88:91], v[156:159], v[190:193], v[88:91]
	v_mfma_f32_16x16x32_bf16 v[84:87], v[132:135], v[198:201], v[84:87]
	v_mfma_f32_16x16x32_bf16 v[80:83], v[156:159], v[198:201], v[80:83]
	v_mfma_f32_16x16x32_bf16 v[76:79], v[132:135], v[206:209], v[76:79]
	v_mfma_f32_16x16x32_bf16 v[72:75], v[156:159], v[206:209], v[72:75]
	v_mfma_f32_16x16x32_bf16 v[64:67], v[132:135], v[214:217], v[64:67]
	v_mfma_f32_16x16x32_bf16 v[56:59], v[156:159], v[214:217], v[56:59]
	s_setprio 0
	s_setprio 1
	v_mfma_f32_16x16x32_bf16 v[28:31], v[160:163], v[186:189], v[28:31]
	v_mfma_f32_16x16x32_bf16 v[24:27], v[168:171], v[186:189], v[24:27]
	v_mfma_f32_16x16x32_bf16 v[20:23], v[160:163], v[194:197], v[20:23]
	v_mfma_f32_16x16x32_bf16 v[16:19], v[168:171], v[194:197], v[16:19]
	v_mfma_f32_16x16x32_bf16 v[12:15], v[160:163], v[202:205], v[12:15]
	v_mfma_f32_16x16x32_bf16 v[8:11], v[168:171], v[202:205], v[8:11]
	v_mfma_f32_16x16x32_bf16 v[4:7], v[160:163], v[210:213], v[4:7]
	v_mfma_f32_16x16x32_bf16 v[0:3], v[168:171], v[210:213], v[0:3]
	v_mfma_f32_16x16x32_bf16 v[28:31], v[164:167], v[190:193], v[28:31]
	v_mfma_f32_16x16x32_bf16 v[24:27], v[182:185], v[190:193], v[24:27]
	v_mfma_f32_16x16x32_bf16 v[20:23], v[164:167], v[198:201], v[20:23]
	v_mfma_f32_16x16x32_bf16 v[16:19], v[182:185], v[198:201], v[16:19]
	v_mfma_f32_16x16x32_bf16 v[12:15], v[164:167], v[206:209], v[12:15]
	v_mfma_f32_16x16x32_bf16 v[8:11], v[182:185], v[206:209], v[8:11]
	v_mfma_f32_16x16x32_bf16 v[4:7], v[164:167], v[214:217], v[4:7]
	v_mfma_f32_16x16x32_bf16 v[0:3], v[182:185], v[214:217], v[0:3]
	s_setprio 0
	s_barrier
	ds_read_b128 v[128:131], v179
	ds_read_b128 v[132:135], v179 offset:1024
	ds_read_b128 v[152:155], v179 offset:2048
	ds_read_b128 v[156:159], v179 offset:3072
	ds_read_b128 v[160:163], v180
	ds_read_b128 v[164:167], v180 offset:1024
	ds_read_b128 v[168:171], v180 offset:2048
	ds_read_b128 v[182:185], v180 offset:3072
	s_add_u32 s24, s24, 0x160000
	s_addc_u32 s25, s25, 0
	s_mov_b32 m0, s30
	v_lshl_add_u64 v[224:225], s[24:25], 0, v[136:137]
	ds_read_b128 v[186:189], v178 offset:32768
	ds_read_b128 v[190:193], v178 offset:33792
	ds_read_b128 v[194:197], v178 offset:34816
	ds_read_b128 v[198:201], v178 offset:35840
	ds_read_b128 v[202:205], v178 offset:36864
	ds_read_b128 v[206:209], v178 offset:37888
	ds_read_b128 v[210:213], v178 offset:38912
	ds_read_b128 v[214:217], v178 offset:39936
	global_load_lds_dwordx4 v[224:225], off
	v_lshl_add_u64 v[224:225], s[24:25], 0, v[140:141]
	s_mov_b32 m0, s31
	s_nop 0
	global_load_lds_dwordx4 v[224:225], off
	s_waitcnt vmcnt(8)
	s_waitcnt lgkmcnt(0)
	s_setprio 1
	s_barrier
	s_waitcnt lgkmcnt(0)
	v_mfma_f32_16x16x32_bf16 v[124:127], v[128:131], v[186:189], v[124:127]
	v_mfma_f32_16x16x32_bf16 v[120:123], v[152:155], v[186:189], v[120:123]
	v_mfma_f32_16x16x32_bf16 v[116:119], v[128:131], v[194:197], v[116:119]
	v_mfma_f32_16x16x32_bf16 v[112:115], v[152:155], v[194:197], v[112:115]
	v_mfma_f32_16x16x32_bf16 v[108:111], v[128:131], v[202:205], v[108:111]
	v_mfma_f32_16x16x32_bf16 v[104:107], v[152:155], v[202:205], v[104:107]
	v_mfma_f32_16x16x32_bf16 v[100:103], v[128:131], v[210:213], v[100:103]
	v_mfma_f32_16x16x32_bf16 v[96:99], v[152:155], v[210:213], v[96:99]
	v_mfma_f32_16x16x32_bf16 v[124:127], v[132:135], v[190:193], v[124:127]
	v_mfma_f32_16x16x32_bf16 v[120:123], v[156:159], v[190:193], v[120:123]
	v_mfma_f32_16x16x32_bf16 v[116:119], v[132:135], v[198:201], v[116:119]
	v_mfma_f32_16x16x32_bf16 v[112:115], v[156:159], v[198:201], v[112:115]
	v_mfma_f32_16x16x32_bf16 v[108:111], v[132:135], v[206:209], v[108:111]
	v_mfma_f32_16x16x32_bf16 v[104:107], v[156:159], v[206:209], v[104:107]
	v_mfma_f32_16x16x32_bf16 v[100:103], v[132:135], v[214:217], v[100:103]
	v_mfma_f32_16x16x32_bf16 v[96:99], v[156:159], v[214:217], v[96:99]
	s_setprio 0
	s_setprio 1
	v_mfma_f32_16x16x32_bf16 v[68:71], v[160:163], v[186:189], v[68:71]
	v_mfma_f32_16x16x32_bf16 v[60:63], v[168:171], v[186:189], v[60:63]
	v_mfma_f32_16x16x32_bf16 v[52:55], v[160:163], v[194:197], v[52:55]
	v_mfma_f32_16x16x32_bf16 v[48:51], v[168:171], v[194:197], v[48:51]
	v_mfma_f32_16x16x32_bf16 v[44:47], v[160:163], v[202:205], v[44:47]
	v_mfma_f32_16x16x32_bf16 v[40:43], v[168:171], v[202:205], v[40:43]
	v_mfma_f32_16x16x32_bf16 v[36:39], v[160:163], v[210:213], v[36:39]
	v_mfma_f32_16x16x32_bf16 v[32:35], v[168:171], v[210:213], v[32:35]
	v_mfma_f32_16x16x32_bf16 v[68:71], v[164:167], v[190:193], v[68:71]
	v_mfma_f32_16x16x32_bf16 v[60:63], v[182:185], v[190:193], v[60:63]
	v_mfma_f32_16x16x32_bf16 v[52:55], v[164:167], v[198:201], v[52:55]
	v_mfma_f32_16x16x32_bf16 v[48:51], v[182:185], v[198:201], v[48:51]
	v_mfma_f32_16x16x32_bf16 v[44:47], v[164:167], v[206:209], v[44:47]
	v_mfma_f32_16x16x32_bf16 v[40:43], v[182:185], v[206:209], v[40:43]
	v_mfma_f32_16x16x32_bf16 v[36:39], v[164:167], v[214:217], v[36:39]
	v_mfma_f32_16x16x32_bf16 v[32:35], v[182:185], v[214:217], v[32:35]
	s_setprio 0
	s_barrier
; #define PG8_STAGE(bufoff, gbase, voff) do { _Pragma("unroll") for (int _i = 0; _i < 2; ++_i) \
;         __builtin_amdgcn_global_load_lds((const unsigned*)((const char*)(gbase) + (voff)[_i]), (LAS unsigned*)(lds + (bufoff) + ldsw + _i * 8192), 16, 0, 0); } while (0)
; #define PG8_LDA(dst, b, h) do { _Pragma("unroll") for (int m = 0; m < 4; ++m) _Pragma("unroll") for (int k = 0; k < 2; ++k) dst[m][k] = *(const LAS bf16x8*)(lds + PG8_SA(b, h) + aoff + m * 2048 + k * 1024); } while (0)
; #define PG8_MMA(ai, bj, At, Bt) do { __builtin_amdgcn_s_setprio(1); _Pragma("unroll") for (int m = 0; m < 4; ++m) _Pragma("unroll") for (int n = 0; n < 2; ++n) _Pragma("unroll") for (int k = 0; k < 2; ++k) \
;         acc[ai][bj][m][n] = __builtin_amdgcn_mfma_f32_16x16x32_bf16(Bt[n][k], At[m][k], acc[ai][bj][m][n], 0, 0, 0); __builtin_amdgcn_s_setprio(0); } while (0)
; #define PG8_WAIT_V(n) asm volatile("s_waitcnt vmcnt(" #n ")" ::: "memory")
; #define PG8_WAIT_L(n) asm volatile("s_waitcnt lgkmcnt(" #n ")" ::: "memory")
; #define PG8_BAR __builtin_amdgcn_s_barrier()
; #define PG8_SCHED __builtin_amdgcn_sched_barrier(0)
; template <class Epi, class Sched, bool ALIGN_EPI = false, bool SP2 = false>
; __device__ __forceinline__ void gemm_phase(LAS unsigned char* lds, const Gemm g, const Sched& S, const Epi& E) {
;     ...
;         for (int t = 0; t < nt; t += 2) {
;     ...
;             PG8_LDA(At, 1, 1); PG8_STAGE(PG8_SB(1, 0), b3, voffB); PG8_STAGE(PG8_SB(1, 1), b3 + hstepB, voffB); PG8_STAGE(PG8_SA(1, 0), a3, voffA);
;             PG8_WAIT_V(8); PG8_WAIT_L(0); PG8_BAR; PG8_MMA(1, 0, At, B0); PG8_MMA(1, 1, At, B1); PG8_BAR; PG8_SCHED;
	s_add_i32 s24, s42, s27
	v_lshl_add_u64 v[172:173], v[172:173], 0, s[8:9]
	s_mov_b32 m0, s24
	ds_read_b128 v[186:189], v178 offset:49152
	ds_read_b128 v[190:193], v178 offset:50176
	ds_read_b128 v[194:197], v178 offset:51200
	ds_read_b128 v[198:201], v178 offset:52224
	ds_read_b128 v[202:205], v178 offset:53248
	ds_read_b128 v[206:209], v178 offset:54272
	ds_read_b128 v[210:213], v178 offset:55296
	ds_read_b128 v[214:217], v178 offset:56320
	global_load_lds_dwordx4 v[172:173], off
	s_add_i32 m0, s24, 0x2000
	s_add_u32 s22, s22, 0x160080
	v_lshl_add_u64 v[172:173], v[218:219], 0, s[8:9]
	s_addc_u32 s23, s23, 0
	s_add_i32 s24, s43, s27
	global_load_lds_dwordx4 v[172:173], off
	v_lshl_add_u64 v[172:173], s[22:23], 0, v[138:139]
	s_mov_b32 m0, s24
	s_nop 0
	global_load_lds_dwordx4 v[172:173], off
	v_lshl_add_u64 v[172:173], s[22:23], 0, v[142:143]
	s_add_i32 m0, s24, 0x2000
	s_nop 0
	global_load_lds_dwordx4 v[172:173], off
	v_lshl_add_u64 v[172:173], v[220:221], 0, s[8:9]
	s_mov_b32 m0, s36
	s_nop 0
	global_load_lds_dwordx4 v[172:173], off
	v_lshl_add_u64 v[172:173], v[222:223], 0, s[8:9]
	s_mov_b32 m0, s37
	s_nop 0
	global_load_lds_dwordx4 v[172:173], off
	s_waitcnt vmcnt(8)
	s_waitcnt lgkmcnt(0)
	s_setprio 1
	s_barrier
	s_waitcnt lgkmcnt(0)
	v_mfma_f32_16x16x32_bf16 v[92:95], v[128:131], v[186:189], v[92:95]
	v_mfma_f32_16x16x32_bf16 v[88:91], v[152:155], v[186:189], v[88:91]
	v_mfma_f32_16x16x32_bf16 v[84:87], v[128:131], v[194:197], v[84:87]
	v_mfma_f32_16x16x32_bf16 v[80:83], v[152:155], v[194:197], v[80:83]
	v_mfma_f32_16x16x32_bf16 v[76:79], v[128:131], v[202:205], v[76:79]
	v_mfma_f32_16x16x32_bf16 v[72:75], v[152:155], v[202:205], v[72:75]
	v_mfma_f32_16x16x32_bf16 v[64:67], v[128:131], v[210:213], v[64:67]
	v_mfma_f32_16x16x32_bf16 v[56:59], v[152:155], v[210:213], v[56:59]
	v_mfma_f32_16x16x32_bf16 v[92:95], v[132:135], v[190:193], v[92:95]
	v_mfma_f32_16x16x32_bf16 v[88:91], v[156:159], v[190:193], v[88:91]
	v_mfma_f32_16x16x32_bf16 v[84:87], v[132:135], v[198:201], v[84:87]
	v_mfma_f32_16x16x32_bf16 v[80:83], v[156:159], v[198:201], v[80:83]
	v_mfma_f32_16x16x32_bf16 v[76:79], v[132:135], v[206:209], v[76:79]
	v_mfma_f32_16x16x32_bf16 v[72:75], v[156:159], v[206:209], v[72:75]
	v_mfma_f32_16x16x32_bf16 v[64:67], v[132:135], v[214:217], v[64:67]
	v_mfma_f32_16x16x32_bf16 v[56:59], v[156:159], v[214:217], v[56:59]
	s_setprio 0
	s_setprio 1
	v_mfma_f32_16x16x32_bf16 v[28:31], v[160:163], v[186:189], v[28:31]
	v_mfma_f32_16x16x32_bf16 v[24:27], v[168:171], v[186:189], v[24:27]
	v_mfma_f32_16x16x32_bf16 v[20:23], v[160:163], v[194:197], v[20:23]
	v_mfma_f32_16x16x32_bf16 v[16:19], v[168:171], v[194:197], v[16:19]
	v_mfma_f32_16x16x32_bf16 v[12:15], v[160:163], v[202:205], v[12:15]
	v_mfma_f32_16x16x32_bf16 v[8:11], v[168:171], v[202:205], v[8:11]
	v_mfma_f32_16x16x32_bf16 v[4:7], v[160:163], v[210:213], v[4:7]
	v_mfma_f32_16x16x32_bf16 v[0:3], v[168:171], v[210:213], v[0:3]
	v_mfma_f32_16x16x32_bf16 v[28:31], v[164:167], v[190:193], v[28:31]
	v_mfma_f32_16x16x32_bf16 v[24:27], v[182:185], v[190:193], v[24:27]
	v_mfma_f32_16x16x32_bf16 v[20:23], v[164:167], v[198:201], v[20:23]
	v_mfma_f32_16x16x32_bf16 v[16:19], v[182:185], v[198:201], v[16:19]
	v_mfma_f32_16x16x32_bf16 v[12:15], v[164:167], v[206:209], v[12:15]
	v_mfma_f32_16x16x32_bf16 v[8:11], v[182:185], v[206:209], v[8:11]
	v_mfma_f32_16x16x32_bf16 v[4:7], v[164:167], v[214:217], v[4:7]
	v_mfma_f32_16x16x32_bf16 v[0:3], v[182:185], v[214:217], v[0:3]
	s_setprio 0
	s_barrier
	s_add_i32 s49, s49, 2
	s_add_u32 s20, s20, 0x100
	s_addc_u32 s21, s21, 0
	s_add_u32 s47, s47, 0x100
	s_addc_u32 s48, s48, 0
	s_cmpk_gt_u32 s49, 0x55
	s_cbranch_scc0 .LBB0_1138
	s_and_b64 vcc, exec, s[10:11]
	s_cbranch_vccz .LBB0_1141
	s_barrier
